# combo1
# speedup vs baseline: 1.0102x; 1.0054x over previous
; #define STAGE(P, BASE, br, kt) do { const char* _gb = (const char*)(BASE) + ((size_t)(br) * K + (size_t)(kt) * BK) * 2; \
;     __builtin_amdgcn_global_load_lds((const unsigned*)(_gb + loff0), (unsigned*)((char*)(P) + tid * 16), 16, 0, 0); \
;     __builtin_amdgcn_global_load_lds((const unsigned*)(_gb + (size_t)K * 128 + loff0), (unsigned*)((char*)(P) + tid * 16 + 8192), 16, 0, 0); } while (0)
; #define WAIT_V(n) asm volatile("s_waitcnt vmcnt(" #n ")" ::: "memory")
; #define BAR __builtin_amdgcn_s_barrier()
; template <int EPI> ...
;     ...
;   WAIT_V(4); BAR;
;   STAGE(SB(1, 0), Bt, bcol, 1); STAGE(SA(1, 0), A, brow, 1); STAGE(SB(1, 1), Bt, bcol + HALF, 1);
;   WAIT_V(6); BAR;
.LBB0_276:
	s_or_b64 exec, exec, s[72:73]
	v_readfirstlane_b32 s67, v144
	v_lshl_add_u64 v[6:7], v[0:1], 0, s[12:13]
	s_mov_b32 m0, s67
	v_readfirstlane_b32 s67, v145
	s_waitcnt vmcnt(4)
	s_barrier
	global_load_lds_dwordx4 v[6:7], off
	v_lshl_add_u64 v[0:1], v[0:1], 0, s[16:17]
	s_mov_b32 m0, s67
	v_readfirstlane_b32 s67, v146
	global_load_lds_dwordx4 v[0:1], off
	v_lshl_add_u64 v[0:1], v[2:3], 0, s[12:13]
	s_mov_b32 m0, s67
	v_readfirstlane_b32 s67, v147
	global_load_lds_dwordx4 v[0:1], off
	v_lshl_add_u64 v[0:1], v[2:3], 0, s[16:17]
	s_mov_b32 m0, s67
	v_readfirstlane_b32 s67, v148
	global_load_lds_dwordx4 v[0:1], off
	v_lshl_add_u64 v[0:1], v[4:5], 0, s[12:13]
	s_mov_b32 m0, s67
	v_readfirstlane_b32 s67, v149
	global_load_lds_dwordx4 v[0:1], off
	v_lshl_add_u64 v[0:1], v[4:5], 0, s[16:17]
	s_mov_b32 m0, s67
	s_add_u32 s70, s6, s70
	global_load_lds_dwordx4 v[0:1], off
	v_mov_b32_e32 v0, 0
	s_addc_u32 s71, s7, s71
	s_mov_b32 s67, -2
	v_mov_b32_e32 v1, v0
	v_mov_b32_e32 v2, v0
	v_mov_b32_e32 v3, v0
	v_mov_b32_e32 v4, v0
	v_mov_b32_e32 v5, v0
	v_mov_b32_e32 v6, v0
	v_mov_b32_e32 v7, v0
	v_mov_b32_e32 v8, v0
	v_mov_b32_e32 v9, v0
	v_mov_b32_e32 v10, v0
	v_mov_b32_e32 v11, v0
	v_mov_b32_e32 v12, v0
	v_mov_b32_e32 v13, v0
	v_mov_b32_e32 v14, v0
	v_mov_b32_e32 v15, v0
	v_mov_b32_e32 v16, v0
	v_mov_b32_e32 v17, v0
	v_mov_b32_e32 v18, v0
	v_mov_b32_e32 v19, v0
	v_mov_b32_e32 v20, v0
	v_mov_b32_e32 v21, v0
	v_mov_b32_e32 v22, v0
	v_mov_b32_e32 v23, v0
	v_mov_b32_e32 v24, v0
	v_mov_b32_e32 v25, v0
	v_mov_b32_e32 v26, v0
	v_mov_b32_e32 v27, v0
	v_mov_b32_e32 v28, v0
	v_mov_b32_e32 v29, v0
	v_mov_b32_e32 v30, v0
	v_mov_b32_e32 v31, v0
	v_mov_b32_e32 v32, v0
	v_mov_b32_e32 v33, v0
	v_mov_b32_e32 v34, v0
	v_mov_b32_e32 v35, v0
	v_mov_b32_e32 v36, v0
	v_mov_b32_e32 v37, v0
	v_mov_b32_e32 v38, v0
	v_mov_b32_e32 v39, v0
	v_mov_b32_e32 v40, v0
	v_mov_b32_e32 v41, v0
	v_mov_b32_e32 v42, v0
	v_mov_b32_e32 v43, v0
	v_mov_b32_e32 v44, v0
	v_mov_b32_e32 v45, v0
	v_mov_b32_e32 v46, v0
	v_mov_b32_e32 v47, v0
	v_mov_b32_e32 v48, v0
	v_mov_b32_e32 v49, v0
	v_mov_b32_e32 v50, v0
	v_mov_b32_e32 v51, v0
	v_mov_b32_e32 v52, v0
	v_mov_b32_e32 v53, v0
	v_mov_b32_e32 v54, v0
	v_mov_b32_e32 v55, v0
	v_mov_b32_e32 v56, v0
	v_mov_b32_e32 v57, v0
	v_mov_b32_e32 v58, v0
	v_mov_b32_e32 v59, v0
	v_mov_b32_e32 v60, v0
	v_mov_b32_e32 v61, v0
	v_mov_b32_e32 v62, v0
	v_mov_b32_e32 v63, v0
	v_mov_b32_e32 v64, v0
	v_mov_b32_e32 v65, v0
	v_mov_b32_e32 v66, v0
	v_mov_b32_e32 v67, v0
	v_mov_b32_e32 v68, v0
	v_mov_b32_e32 v69, v0
	v_mov_b32_e32 v70, v0
	v_mov_b32_e32 v71, v0
	v_mov_b32_e32 v72, v0
	v_mov_b32_e32 v73, v0
	v_mov_b32_e32 v74, v0
	v_mov_b32_e32 v75, v0
	v_mov_b32_e32 v76, v0
	v_mov_b32_e32 v77, v0
	v_mov_b32_e32 v78, v0
	v_mov_b32_e32 v79, v0
	v_mov_b32_e32 v80, v0
	v_mov_b32_e32 v81, v0
	v_mov_b32_e32 v82, v0
	v_mov_b32_e32 v83, v0
	v_mov_b32_e32 v84, v0
	v_mov_b32_e32 v85, v0
	v_mov_b32_e32 v86, v0
	v_mov_b32_e32 v87, v0
	v_mov_b32_e32 v88, v0
	v_mov_b32_e32 v89, v0
	v_mov_b32_e32 v90, v0
	v_mov_b32_e32 v91, v0
	v_mov_b32_e32 v92, v0
	v_mov_b32_e32 v93, v0
	v_mov_b32_e32 v94, v0
	v_mov_b32_e32 v95, v0
	v_mov_b32_e32 v96, v0
	v_mov_b32_e32 v97, v0
	v_mov_b32_e32 v98, v0
	v_mov_b32_e32 v99, v0
	v_mov_b32_e32 v100, v0
	v_mov_b32_e32 v101, v0
	v_mov_b32_e32 v102, v0
	v_mov_b32_e32 v103, v0
	v_mov_b32_e32 v104, v0
	v_mov_b32_e32 v105, v0
	v_mov_b32_e32 v106, v0
	v_mov_b32_e32 v107, v0
	v_mov_b32_e32 v108, v0
	v_mov_b32_e32 v109, v0
	v_mov_b32_e32 v110, v0
	v_mov_b32_e32 v111, v0
	v_mov_b32_e32 v112, v0
	v_mov_b32_e32 v113, v0
	v_mov_b32_e32 v114, v0
	v_mov_b32_e32 v115, v0
	v_mov_b32_e32 v116, v0
	v_mov_b32_e32 v117, v0
	v_mov_b32_e32 v118, v0
	v_mov_b32_e32 v119, v0
	v_mov_b32_e32 v120, v0
	v_mov_b32_e32 v121, v0
	v_mov_b32_e32 v122, v0
	v_mov_b32_e32 v123, v0
	v_mov_b32_e32 v124, v0
	v_mov_b32_e32 v125, v0
	v_mov_b32_e32 v126, v0
	v_mov_b32_e32 v127, v0
	s_waitcnt vmcnt(6)
	s_barrier

; #define STAGE(P, BASE, br, kt) do { const char* _gb = (const char*)(BASE) + ((size_t)(br) * K + (size_t)(kt) * BK) * 2; \
;     __builtin_amdgcn_global_load_lds((const unsigned*)(_gb + loff0), (unsigned*)((char*)(P) + tid * 16), 16, 0, 0); \
;     __builtin_amdgcn_global_load_lds((const unsigned*)(_gb + (size_t)K * 128 + loff0), (unsigned*)((char*)(P) + tid * 16 + 8192), 16, 0, 0); } while (0)
; #define WAIT_V(n) asm volatile("s_waitcnt vmcnt(" #n ")" ::: "memory")
; #define BAR __builtin_amdgcn_s_barrier()
; template <int EPI> ...
;     ...
;   WAIT_V(4); BAR;
;   STAGE(SB(1, 0), Bt, bcol, 1); STAGE(SA(1, 0), A, brow, 1); STAGE(SB(1, 1), Bt, bcol + HALF, 1);
;   WAIT_V(6); BAR;
.LBB0_323:
	s_or_b64 exec, exec, s[64:65]
	v_readfirstlane_b32 s64, v143
	v_lshl_add_u64 v[6:7], v[0:1], 0, s[10:11]
	s_mov_b32 m0, s64
	v_readfirstlane_b32 s64, v144
	s_waitcnt vmcnt(4)
	s_barrier
	global_load_lds_dwordx4 v[6:7], off
	v_lshl_add_u64 v[0:1], v[0:1], 0, s[12:13]
	s_mov_b32 m0, s64
	v_readfirstlane_b32 s64, v145
	global_load_lds_dwordx4 v[0:1], off
	v_lshl_add_u64 v[0:1], v[2:3], 0, s[10:11]
	s_mov_b32 m0, s64
	v_readfirstlane_b32 s64, v146
	global_load_lds_dwordx4 v[0:1], off
	v_lshl_add_u64 v[0:1], v[2:3], 0, s[12:13]
	s_mov_b32 m0, s64
	v_readfirstlane_b32 s64, v147
	global_load_lds_dwordx4 v[0:1], off
	v_lshl_add_u64 v[0:1], v[4:5], 0, s[10:11]
	s_mov_b32 m0, s64
	v_readfirstlane_b32 s64, v148
	global_load_lds_dwordx4 v[0:1], off
	v_lshl_add_u64 v[0:1], v[4:5], 0, s[12:13]
	s_mov_b32 m0, s64
	s_ashr_i32 s61, s60, 31
	global_load_lds_dwordx4 v[0:1], off
	s_add_u32 s62, s6, s62
	s_addc_u32 s63, s7, s63
	s_add_u32 s64, s6, s77
	s_addc_u32 s65, s7, s76
	s_add_u32 s66, s6, s66
	v_mov_b32_e32 v0, 0
	s_addc_u32 s67, s7, s67
	s_mov_b32 s76, -2
	v_mov_b32_e32 v1, v0
	v_mov_b32_e32 v2, v0
	v_mov_b32_e32 v3, v0
	v_mov_b32_e32 v4, v0
	v_mov_b32_e32 v5, v0
	v_mov_b32_e32 v6, v0
	v_mov_b32_e32 v7, v0
	v_mov_b32_e32 v8, v0
	v_mov_b32_e32 v9, v0
	v_mov_b32_e32 v10, v0
	v_mov_b32_e32 v11, v0
	v_mov_b32_e32 v12, v0
	v_mov_b32_e32 v13, v0
	v_mov_b32_e32 v14, v0
	v_mov_b32_e32 v15, v0
	v_mov_b32_e32 v16, v0
	v_mov_b32_e32 v17, v0
	v_mov_b32_e32 v18, v0
	v_mov_b32_e32 v19, v0
	v_mov_b32_e32 v20, v0
	v_mov_b32_e32 v21, v0
	v_mov_b32_e32 v22, v0
	v_mov_b32_e32 v23, v0
	v_mov_b32_e32 v24, v0
	v_mov_b32_e32 v25, v0
	v_mov_b32_e32 v26, v0
	v_mov_b32_e32 v27, v0
	v_mov_b32_e32 v28, v0
	v_mov_b32_e32 v29, v0
	v_mov_b32_e32 v30, v0
	v_mov_b32_e32 v31, v0
	v_mov_b32_e32 v32, v0
	v_mov_b32_e32 v33, v0
	v_mov_b32_e32 v34, v0
	v_mov_b32_e32 v35, v0
	v_mov_b32_e32 v36, v0
	v_mov_b32_e32 v37, v0
	v_mov_b32_e32 v38, v0
	v_mov_b32_e32 v39, v0
	v_mov_b32_e32 v40, v0
	v_mov_b32_e32 v41, v0
	v_mov_b32_e32 v42, v0
	v_mov_b32_e32 v43, v0
	v_mov_b32_e32 v44, v0
	v_mov_b32_e32 v45, v0
	v_mov_b32_e32 v46, v0
	v_mov_b32_e32 v47, v0
	v_mov_b32_e32 v48, v0
	v_mov_b32_e32 v49, v0
	v_mov_b32_e32 v50, v0
	v_mov_b32_e32 v51, v0
	v_mov_b32_e32 v52, v0
	v_mov_b32_e32 v53, v0
	v_mov_b32_e32 v54, v0
	v_mov_b32_e32 v55, v0
	v_mov_b32_e32 v56, v0
	v_mov_b32_e32 v57, v0
	v_mov_b32_e32 v58, v0
	v_mov_b32_e32 v59, v0
	v_mov_b32_e32 v60, v0
	v_mov_b32_e32 v61, v0
	v_mov_b32_e32 v62, v0
	v_mov_b32_e32 v63, v0
	v_mov_b32_e32 v64, v0
	v_mov_b32_e32 v65, v0
	v_mov_b32_e32 v66, v0
	v_mov_b32_e32 v67, v0
	v_mov_b32_e32 v68, v0
	v_mov_b32_e32 v69, v0
	v_mov_b32_e32 v70, v0
	v_mov_b32_e32 v71, v0
	v_mov_b32_e32 v72, v0
	v_mov_b32_e32 v73, v0
	v_mov_b32_e32 v74, v0
	v_mov_b32_e32 v75, v0
	v_mov_b32_e32 v76, v0
	v_mov_b32_e32 v77, v0
	v_mov_b32_e32 v78, v0
	v_mov_b32_e32 v79, v0
	v_mov_b32_e32 v80, v0
	v_mov_b32_e32 v81, v0
	v_mov_b32_e32 v82, v0
	v_mov_b32_e32 v83, v0
	v_mov_b32_e32 v84, v0
	v_mov_b32_e32 v85, v0
	v_mov_b32_e32 v86, v0
	v_mov_b32_e32 v87, v0
	v_mov_b32_e32 v88, v0
	v_mov_b32_e32 v89, v0
	v_mov_b32_e32 v90, v0
	v_mov_b32_e32 v91, v0
	v_mov_b32_e32 v92, v0
	v_mov_b32_e32 v93, v0
	v_mov_b32_e32 v94, v0
	v_mov_b32_e32 v95, v0
	v_mov_b32_e32 v96, v0
	v_mov_b32_e32 v97, v0
	v_mov_b32_e32 v98, v0
	v_mov_b32_e32 v99, v0
	v_mov_b32_e32 v100, v0
	v_mov_b32_e32 v101, v0
	v_mov_b32_e32 v102, v0
	v_mov_b32_e32 v103, v0
	v_mov_b32_e32 v104, v0
	v_mov_b32_e32 v105, v0
	v_mov_b32_e32 v106, v0
	v_mov_b32_e32 v107, v0
	v_mov_b32_e32 v108, v0
	v_mov_b32_e32 v109, v0
	v_mov_b32_e32 v110, v0
	v_mov_b32_e32 v111, v0
	v_mov_b32_e32 v112, v0
	v_mov_b32_e32 v113, v0
	v_mov_b32_e32 v114, v0
	v_mov_b32_e32 v115, v0
	v_mov_b32_e32 v116, v0
	v_mov_b32_e32 v117, v0
	v_mov_b32_e32 v118, v0
	v_mov_b32_e32 v119, v0
	v_mov_b32_e32 v120, v0
	v_mov_b32_e32 v121, v0
	v_mov_b32_e32 v122, v0
	v_mov_b32_e32 v123, v0
	v_mov_b32_e32 v124, v0
	v_mov_b32_e32 v125, v0
	v_mov_b32_e32 v126, v0
	v_mov_b32_e32 v127, v0
	s_waitcnt vmcnt(6)
	s_barrier

; #define STAGE(P, BASE, br, kt) do { const char* _gb = (const char*)(BASE) + ((size_t)(br) * K + (size_t)(kt) * BK) * 2; \
;     __builtin_amdgcn_global_load_lds((const unsigned*)(_gb + loff0), (unsigned*)((char*)(P) + tid * 16), 16, 0, 0); \
;     __builtin_amdgcn_global_load_lds((const unsigned*)(_gb + (size_t)K * 128 + loff0), (unsigned*)((char*)(P) + tid * 16 + 8192), 16, 0, 0); } while (0)
; #define WAIT_V(n) asm volatile("s_waitcnt vmcnt(" #n ")" ::: "memory")
; #define BAR __builtin_amdgcn_s_barrier()
; template <int EPI> ...
;     ...
;   WAIT_V(4); BAR;
;   STAGE(SB(1, 0), Bt, bcol, 1); STAGE(SA(1, 0), A, brow, 1); STAGE(SB(1, 1), Bt, bcol + HALF, 1);
;   WAIT_V(6); BAR;
.LBB0_410:
	s_or_b64 exec, exec, s[70:71]
	v_readfirstlane_b32 s61, v143
	v_lshl_add_u64 v[6:7], v[0:1], 0, s[10:11]
	s_mov_b32 m0, s61
	v_readfirstlane_b32 s61, v144
	s_waitcnt vmcnt(4)
	s_barrier
	global_load_lds_dwordx4 v[6:7], off
	v_lshl_add_u64 v[0:1], v[0:1], 0, s[12:13]
	s_mov_b32 m0, s61
	v_readfirstlane_b32 s61, v145
	global_load_lds_dwordx4 v[0:1], off
	v_lshl_add_u64 v[0:1], v[2:3], 0, s[10:11]
	s_mov_b32 m0, s61
	v_readfirstlane_b32 s61, v146
	global_load_lds_dwordx4 v[0:1], off
	v_lshl_add_u64 v[0:1], v[2:3], 0, s[12:13]
	s_mov_b32 m0, s61
	v_readfirstlane_b32 s61, v147
	global_load_lds_dwordx4 v[0:1], off
	v_lshl_add_u64 v[0:1], v[4:5], 0, s[10:11]
	s_mov_b32 m0, s61
	v_readfirstlane_b32 s61, v148
	global_load_lds_dwordx4 v[0:1], off
	v_lshl_add_u64 v[0:1], v[4:5], 0, s[12:13]
	s_mov_b32 m0, s61
	s_add_u32 s66, s6, s66
	global_load_lds_dwordx4 v[0:1], off
	s_addc_u32 s67, s7, s67
	s_add_u32 s68, s6, s68
	v_mov_b32_e32 v0, 0
	s_addc_u32 s69, s7, s69
	s_mov_b32 s61, -2
	v_mov_b32_e32 v1, v0
	v_mov_b32_e32 v2, v0
	v_mov_b32_e32 v3, v0
	v_mov_b32_e32 v4, v0
	v_mov_b32_e32 v5, v0
	v_mov_b32_e32 v6, v0
	v_mov_b32_e32 v7, v0
	v_mov_b32_e32 v8, v0
	v_mov_b32_e32 v9, v0
	v_mov_b32_e32 v10, v0
	v_mov_b32_e32 v11, v0
	v_mov_b32_e32 v12, v0
	v_mov_b32_e32 v13, v0
	v_mov_b32_e32 v14, v0
	v_mov_b32_e32 v15, v0
	v_mov_b32_e32 v16, v0
	v_mov_b32_e32 v17, v0
	v_mov_b32_e32 v18, v0
	v_mov_b32_e32 v19, v0
	v_mov_b32_e32 v20, v0
	v_mov_b32_e32 v21, v0
	v_mov_b32_e32 v22, v0
	v_mov_b32_e32 v23, v0
	v_mov_b32_e32 v24, v0
	v_mov_b32_e32 v25, v0
	v_mov_b32_e32 v26, v0
	v_mov_b32_e32 v27, v0
	v_mov_b32_e32 v28, v0
	v_mov_b32_e32 v29, v0
	v_mov_b32_e32 v30, v0
	v_mov_b32_e32 v31, v0
	v_mov_b32_e32 v32, v0
	v_mov_b32_e32 v33, v0
	v_mov_b32_e32 v34, v0
	v_mov_b32_e32 v35, v0
	v_mov_b32_e32 v36, v0
	v_mov_b32_e32 v37, v0
	v_mov_b32_e32 v38, v0
	v_mov_b32_e32 v39, v0
	v_mov_b32_e32 v40, v0
	v_mov_b32_e32 v41, v0
	v_mov_b32_e32 v42, v0
	v_mov_b32_e32 v43, v0
	v_mov_b32_e32 v44, v0
	v_mov_b32_e32 v45, v0
	v_mov_b32_e32 v46, v0
	v_mov_b32_e32 v47, v0
	v_mov_b32_e32 v48, v0
	v_mov_b32_e32 v49, v0
	v_mov_b32_e32 v50, v0
	v_mov_b32_e32 v51, v0
	v_mov_b32_e32 v52, v0
	v_mov_b32_e32 v53, v0
	v_mov_b32_e32 v54, v0
	v_mov_b32_e32 v55, v0
	v_mov_b32_e32 v56, v0
	v_mov_b32_e32 v57, v0
	v_mov_b32_e32 v58, v0
	v_mov_b32_e32 v59, v0
	v_mov_b32_e32 v60, v0
	v_mov_b32_e32 v61, v0
	v_mov_b32_e32 v62, v0
	v_mov_b32_e32 v63, v0
	v_mov_b32_e32 v64, v0
	v_mov_b32_e32 v65, v0
	v_mov_b32_e32 v66, v0
	v_mov_b32_e32 v67, v0
	v_mov_b32_e32 v68, v0
	v_mov_b32_e32 v69, v0
	v_mov_b32_e32 v70, v0
	v_mov_b32_e32 v71, v0
	v_mov_b32_e32 v72, v0
	v_mov_b32_e32 v73, v0
	v_mov_b32_e32 v74, v0
	v_mov_b32_e32 v75, v0
	v_mov_b32_e32 v76, v0
	v_mov_b32_e32 v77, v0
	v_mov_b32_e32 v78, v0
	v_mov_b32_e32 v79, v0
	v_mov_b32_e32 v80, v0
	v_mov_b32_e32 v81, v0
	v_mov_b32_e32 v82, v0
	v_mov_b32_e32 v83, v0
	v_mov_b32_e32 v84, v0
	v_mov_b32_e32 v85, v0
	v_mov_b32_e32 v86, v0
	v_mov_b32_e32 v87, v0
	v_mov_b32_e32 v88, v0
	v_mov_b32_e32 v89, v0
	v_mov_b32_e32 v90, v0
	v_mov_b32_e32 v91, v0
	v_mov_b32_e32 v92, v0
	v_mov_b32_e32 v93, v0
	v_mov_b32_e32 v94, v0
	v_mov_b32_e32 v95, v0
	v_mov_b32_e32 v96, v0
	v_mov_b32_e32 v97, v0
	v_mov_b32_e32 v98, v0
	v_mov_b32_e32 v99, v0
	v_mov_b32_e32 v100, v0
	v_mov_b32_e32 v101, v0
	v_mov_b32_e32 v102, v0
	v_mov_b32_e32 v103, v0
	v_mov_b32_e32 v104, v0
	v_mov_b32_e32 v105, v0
	v_mov_b32_e32 v106, v0
	v_mov_b32_e32 v107, v0
	v_mov_b32_e32 v108, v0
	v_mov_b32_e32 v109, v0
	v_mov_b32_e32 v110, v0
	v_mov_b32_e32 v111, v0
	v_mov_b32_e32 v112, v0
	v_mov_b32_e32 v113, v0
	v_mov_b32_e32 v114, v0
	v_mov_b32_e32 v115, v0
	v_mov_b32_e32 v116, v0
	v_mov_b32_e32 v117, v0
	v_mov_b32_e32 v118, v0
	v_mov_b32_e32 v119, v0
	v_mov_b32_e32 v120, v0
	v_mov_b32_e32 v121, v0
	v_mov_b32_e32 v122, v0
	v_mov_b32_e32 v123, v0
	v_mov_b32_e32 v124, v0
	v_mov_b32_e32 v125, v0
	v_mov_b32_e32 v126, v0
	v_mov_b32_e32 v127, v0
	s_waitcnt vmcnt(6)
	s_barrier

; __device__ __forceinline__ void phase_scan(const Params& p, int bid, int nblk, int wv) {
;     ...
;   int tid = opaque_tid(wv), lane = tid & 63, wave = tid >> 6;
;   const bool consumer = wave < 4;
;   const int kq = lane & 7, row0 = (wave & 3) * 16 + (lane >> 3) * 2;
;   const int ptid = tid & 255, s1 = ptid >> 3, c8 = ptid & 7;
;   constexpr int NCH = S_ / 32;
;   for (int hh = bid; hh < NB_ * NH_; hh += nblk) {
;     int b = hh / NH_, h = hh % NH_;
;     int ch0 = h * 64 + c8 * 8;
;     float* Lc = L + 2 * SC_BUF;
;     __syncthreads();
;     for (int e = tid; e < 640; e += 512) {
;       int a = e >> 6, ch = h * 64 + (e & 63);
;       float v;
;       if (a == 0) v = p.in[10][ch]; else if (a == 1) v = p.in[10][R_ + ch]; else if (a == 2) v = p.in[10][2 * R_ + ch];
;       else if (a == 3) v = p.in[13][ch]; else if (a == 4) v = p.in[15][ch]; else if (a == 5) v = p.in[18][ch];
;       else if (a == 6) v = p.in[19][ch]; else if (a == 7) v = p.in[20][ch]; else if (a == 8) v = p.in[21][ch];
;       else v = p.in[22][ch];
;       Lc[e] = v;
;     }
;     __syncthreads();
;     f32x2 S0[4], S1[4];
; #pragma unroll
;     for (int i = 0; i < 4; ++i) { S0[i] = f32x2{0.f, 0.f}; S1[i] = f32x2{0.f, 0.f}; }
;     float ym[8];
; #pragma unroll
;     for (int j = 0; j < 8; ++j) { ym[j] = (kq == j) ? 1.f : 0.f; asm volatile("" : "+v"(ym[j])); }
.LBB0_889:
	s_or_b64 exec, exec, s[2:3]
	s_mov_b64 s[46:47], s[0:1]
	s_barrier
	s_load_dwordx4 s[36:39], s[46:47], 0x60
	s_load_dwordx16 s[16:31], s[46:47], 0x90
	s_load_dwordx2 s[12:13], s[46:47], 0xe0
	s_cmpk_lt_i32 s33, 0xc1
	s_cselect_b64 s[2:3], -1, 0
	s_cmpk_lt_i32 s91, 0xc0
	s_cselect_b64 s[4:5], -1, 0
	s_or_b64 s[4:5], s[4:5], s[2:3]
	s_mov_b64 s[2:3], -1
	s_and_b64 vcc, exec, s[4:5]
	s_cbranch_vccz .LBB0_951
	s_cmpk_gt_i32 s91, 0xbf
	v_writelane_b32 v255, s82, 0
	s_mov_b32 s82, s80
	v_mbcnt_lo_u32_b32 v0, -1, 0
	v_mbcnt_hi_u32_b32 v0, -1, v0
	s_cbranch_scc1 .LBB0_950
	v_or_b32_e32 v89, s15, v0
	v_lshrrev_b32_e32 v1, 2, v89
	v_and_b32_e32 v151, 62, v1
	v_and_b32_e32 v1, 7, v0
	s_waitcnt lgkmcnt(0)
	s_add_u32 s50, s12, 0x12af0000
	v_cmp_eq_u32_e32 vcc, 1, v1
	s_addc_u32 s51, s13, 0
	s_add_u32 s52, s12, 0x28af0000
	v_cndmask_b32_e64 v179, 0, 1.0, vcc
	v_cmp_eq_u32_e32 vcc, 2, v1
	s_addc_u32 s53, s13, 0
	s_add_i32 s8, 0, 0x1cc00
	v_cndmask_b32_e64 v180, 0, 1.0, vcc
	v_cmp_eq_u32_e32 vcc, 3, v1
	v_lshlrev_b32_e32 v165, 5, v1
	v_add_u32_e32 v166, s8, v165
	v_cndmask_b32_e64 v181, 0, 1.0, vcc
	v_cmp_eq_u32_e32 vcc, 4, v1
	s_add_i32 s8, 0, 0x1cd00
	v_add_u32_e32 v167, s8, v165
	v_cndmask_b32_e64 v182, 0, 1.0, vcc
	v_cmp_eq_u32_e32 vcc, 5, v1
	s_add_i32 s8, 0, 0x1c600
	v_add_u32_e32 v168, s8, v165
	v_cndmask_b32_e64 v183, 0, 1.0, vcc
	v_cmp_eq_u32_e32 vcc, 6, v1
	s_add_i32 s8, 0, 0x1c700
	v_bfe_u32 v2, v89, 3, 3
	v_lshlrev_b32_e32 v4, 2, v89
	v_cndmask_b32_e64 v184, 0, 1.0, vcc
	v_cmp_eq_u32_e32 vcc, 7, v1
	v_add_u32_e32 v170, s8, v165
	s_add_i32 s8, 0, 0x1ce00
	v_and_b32_e32 v5, 0x300, v4
	v_cndmask_b32_e64 v185, 0, 1.0, vcc
	v_cmp_eq_u32_e32 vcc, 0, v2
	v_add3_u32 v171, s8, v5, v165
	s_add_i32 s8, 0, 0x1c500
	v_cndmask_b32_e64 v187, 1.0, 0, vcc
	v_cmp_gt_u32_e32 vcc, 2, v2
	v_add_u32_e32 v172, s8, v165
	s_add_i32 s8, 0, 0x1c800
	v_cndmask_b32_e64 v90, 1.0, 0, vcc
	v_cmp_gt_u32_e32 vcc, 4, v2
	s_load_dwordx2 s[48:49], s[46:47], 0x78
	v_add_u32_e32 v173, s8, v165
	s_add_i32 s8, 0, 0x1c900
	v_cndmask_b32_e64 v93, 1.0, 0, vcc
	v_cmp_gt_u32_e32 vcc, 3, v2
	v_add_u32_e32 v174, s8, v165
	s_add_i32 s8, 0, 0x1ca00
	v_cndmask_b32_e64 v92, 1.0, 0, vcc
	v_cmp_gt_u32_e32 vcc, 6, v2
	v_bfe_u32 v88, v89, 3, 5
	s_add_i32 s14, 0, 0x1c400
	v_add_u32_e32 v175, s8, v165
	s_add_i32 s8, 0, 0x1cb00
	v_cndmask_b32_e64 v95, 1.0, 0, vcc
	v_cmp_gt_u32_e32 vcc, 5, v2
	s_movk_i32 s2, 0xff
	v_lshlrev_b32_e32 v161, 3, v1
	s_movk_i32 s4, 0x280
	v_add_u32_e32 v169, s14, v165
	v_lshlrev_b32_e32 v3, 3, v88
	v_add_u32_e32 v176, s8, v165
	v_lshlrev_b32_e32 v5, 8, v1
	v_and_b32_e32 v177, 63, v0
	v_cmp_eq_u32_e64 s[8:9], 0, v1
	v_lshlrev_b32_e32 v0, 5, v89
	v_cndmask_b32_e64 v94, 1.0, 0, vcc
	v_cmp_eq_u32_e64 s[10:11], 7, v2
	v_add_u32_e32 v189, s14, v4
	s_mov_b32 s14, 0xc000
	v_cmp_lt_u32_e64 s[2:3], s2, v89
	v_cmp_gt_u32_e64 s[4:5], s4, v89
	v_mov_b32_e32 v19, 0
	s_mov_b32 s55, 0
	v_cmp_ne_u32_e64 s[6:7], 0, v88
	v_or_b32_e32 v162, 32, v88
	v_lshl_or_b32 v163, v88, 6, v161
	v_lshlrev_b32_e32 v164, 4, v88
	v_cndmask_b32_e64 v178, 0, 1.0, s[8:9]
	v_and_b32_e32 v186, 0x1800, v0
	v_cndmask_b32_e64 v97, 0, 1.0, s[10:11]
	v_mov_b32_e32 v96, v95
	v_pk_mov_b32 v[98:99], v[92:93], v[94:95] op_sel:[1,0]
	v_mov_b32_e32 v91, v92
	v_lshrrev_b32_e32 v188, 6, v89
	v_or3_b32 v190, v5, v3, s14
	v_or_b32_e32 v191, 0xa100, v3
	v_or_b32_e32 v192, 0x100, v165
	v_lshlrev_b32_e32 v198, 2, v151
	s_mov_b32 s98, 0x1010101
	s_mov_b32 s99, 0x1010101
	s_mov_b64 s[56:57], 0x3000
	s_mov_b64 s[58:59], 0x1800
	s_movk_i32 s43, 0x7f
	s_movk_i32 s63, 0x2c00
	s_mov_b64 s[60:61], 0x400
	s_movk_i32 s92, 0x1000
	s_movk_i32 s93, 0xe000
	s_movk_i32 s94, 0x2400
	s_mov_b32 s95, 0xe200
	v_mov_b32_e32 v193, 0x3a27c5ac
	s_mov_b32 s96, 0x800000
	s_mov_b32 s62, 0xbf1b4598
	s_movk_i32 s97, 0xf000
	s_mov_b32 s14, s91
	s_branch .LBB0_893

; __device__ __forceinline__ void phase_scan(const Params& p, int bid, int nblk, int wv) {
;     ...
;       if (consumer) {
;         if (iv >= 0 && iv < NCH) {
;           float* B = L + (iv & 1) * SC_BUF;
;           const float* q = B + kq * 8;
;           f32x4 kkn0 = *reinterpret_cast<const f32x4*>(q), kkn1 = *reinterpret_cast<const f32x4*>(q + 4);
;           f32x4 wr0 = *reinterpret_cast<const f32x4*>(q + 2048), wr1 = *reinterpret_cast<const f32x4*>(q + 2048 + 4);
;           f32x4 ka0 = *reinterpret_cast<const f32x4*>(q + 6144), ka1 = *reinterpret_cast<const f32x4*>(q + 6144 + 4);
;           f32x4 kp0 = *reinterpret_cast<const f32x4*>(q + 8192), kp1 = *reinterpret_cast<const f32x4*>(q + 8192 + 4);
;           f32x2 vv = *reinterpret_cast<const f32x2*>(B + 10240 + row0);
;           f32x2 cc = *reinterpret_cast<const f32x2*>(B + 14336);
;           const float* We = L + 2 * SC_BUF + 640 + (iv & 1) * 256 + kq * 8;
;           for (int sb = 0; sb < 4; ++sb) {
;           float yk0 = 0.f, yk1 = 0.f;
; #pragma unroll
;           for (int jj = 0; jj < 8; ++jj) {
;             const int s = sb * 8 + jj;
;             const int sn = (s + 1) & 31;
;             const float* qn = q + sn * 64;
;             f32x2 sa0 = S0[0] * kkn0.lo, sa1 = S1[0] * kkn0.lo, yp0 = S0[0] * wr0.lo, yp1 = S1[0] * wr0.lo;
;             sa0 += S0[1] * kkn0.hi; sa1 += S1[1] * kkn0.hi; yp0 += S0[1] * wr0.hi; yp1 += S1[1] * wr0.hi;
;             sa0 += S0[2] * kkn1.lo; sa1 += S1[2] * kkn1.lo; yp0 += S0[2] * wr1.lo; yp1 += S1[2] * wr1.lo;
;             sa0 += S0[3] * kkn1.hi; sa1 += S1[3] * kkn1.hi; yp0 += S0[3] * wr1.hi; yp1 += S1[3] * wr1.hi;
;             kkn0 = *reinterpret_cast<const f32x4*>(qn); kkn1 = *reinterpret_cast<const f32x4*>(qn + 4);
;             wr0 = *reinterpret_cast<const f32x4*>(qn + 2048); wr1 = *reinterpret_cast<const f32x4*>(qn + 2048 + 4);
;             float a0 = reduce8_np(sa0.x + sa0.y), p0 = reduce8_np(yp0.x + yp0.y);
.LBB0_946:
	s_andn2_saveexec_b64 s[68:69], s[68:69]
	s_cbranch_execz .LBB0_931
	s_cmp_lt_i32 s72, 0
	s_cbranch_scc1 .LBB0_931
	s_cmpk_eq_i32 s72, 0x80
	s_cbranch_scc1 .LBB0_931
	s_and_b32 s54, s72, 1
	s_lshl_b32 s70, s54, 10
	s_mul_i32 s54, s54, 0xe200
	s_add_i32 s70, s70, 0x1ce00
	v_add_u32_e32 v200, s54, v165
	v_add_u32_e32 v201, s54, v198
	v_mov_b32_e32 v202, s54
	v_add_u32_e32 v203, s70, v165
	ds_read_b128 v[208:211], v200
	ds_read_b128 v[212:215], v200 offset:16
	ds_read_b128 v[216:219], v200 offset:8192
	ds_read_b128 v[220:223], v200 offset:8208
	ds_read_b128 v[224:227], v200 offset:24576
	ds_read_b128 v[228:231], v200 offset:24592
	ds_read_b128 v[232:235], v200 offset:32768
	ds_read_b128 v[236:239], v200 offset:32784
	ds_read_b64 v[240:241], v201 offset:40960
	ds_read_b64 v[242:243], v202 offset:57344
	s_mov_b32 s100, 4
.Lsc_loop:
	s_waitcnt lgkmcnt(0)
	ds_read_b128 v[56:59], v200 offset:256
	ds_read_b128 v[60:63], v200 offset:272
	ds_read_b128 v[64:67], v200 offset:8448
	ds_read_b128 v[68:71], v200 offset:8464
	ds_read_b128 v[72:75], v200 offset:24832
	ds_read_b128 v[76:79], v200 offset:24848
	ds_read_b128 v[80:83], v200 offset:33024
	ds_read_b128 v[84:87], v200 offset:33040
	ds_read_b64 v[244:245], v201 offset:41216
	ds_read_b64 v[246:247], v202 offset:57360
	v_pk_mul_f32 v[250:251], v[0:1], v[208:209] op_sel_hi:[1,0]
	v_pk_mul_f32 v[252:253], v[0:1], v[216:217] op_sel_hi:[1,0]
	v_pk_fma_f32 v[250:251], v[2:3], v[208:209], v[250:251] op_sel:[0,1,0]
	v_pk_fma_f32 v[252:253], v[2:3], v[216:217], v[252:253] op_sel:[0,1,0]
	v_pk_fma_f32 v[250:251], v[4:5], v[210:211], v[250:251] op_sel_hi:[1,0,1]
	v_pk_fma_f32 v[252:253], v[4:5], v[218:219], v[252:253] op_sel_hi:[1,0,1]
	v_pk_fma_f32 v[250:251], v[6:7], v[210:211], v[250:251] op_sel:[0,1,0]
	v_pk_fma_f32 v[252:253], v[6:7], v[218:219], v[252:253] op_sel:[0,1,0]
	v_pk_fma_f32 v[250:251], v[8:9], v[212:213], v[250:251] op_sel_hi:[1,0,1]
	v_pk_fma_f32 v[252:253], v[8:9], v[220:221], v[252:253] op_sel_hi:[1,0,1]
	v_pk_fma_f32 v[250:251], v[10:11], v[212:213], v[250:251] op_sel:[0,1,0]
	v_pk_fma_f32 v[252:253], v[10:11], v[220:221], v[252:253] op_sel:[0,1,0]
	v_pk_fma_f32 v[250:251], v[12:13], v[214:215], v[250:251] op_sel_hi:[1,0,1]
	v_pk_fma_f32 v[252:253], v[12:13], v[222:223], v[252:253] op_sel_hi:[1,0,1]
	v_pk_fma_f32 v[250:251], v[14:15], v[214:215], v[250:251] op_sel:[0,1,0]
	v_pk_fma_f32 v[252:253], v[14:15], v[222:223], v[252:253] op_sel:[0,1,0]
	v_pk_fma_f32 v[0:1], v[240:241], v[232:233], v[0:1] op_sel_hi:[1,0,1]
	v_add_f32_dpp v250, v250, v250 quad_perm:[1,0,3,2] row_mask:0xf bank_mask:0xf bound_ctrl:1
	v_add_f32_dpp v251, v251, v251 quad_perm:[1,0,3,2] row_mask:0xf bank_mask:0xf bound_ctrl:1
	v_add_f32_dpp v252, v252, v252 quad_perm:[1,0,3,2] row_mask:0xf bank_mask:0xf bound_ctrl:1
	v_add_f32_dpp v253, v253, v253 quad_perm:[1,0,3,2] row_mask:0xf bank_mask:0xf bound_ctrl:1
	v_pk_fma_f32 v[2:3], v[240:241], v[232:233], v[2:3] op_sel:[0,1,0]
	v_pk_fma_f32 v[4:5], v[240:241], v[234:235], v[4:5] op_sel_hi:[1,0,1]
	v_add_f32_dpp v250, v250, v250 quad_perm:[2,3,0,1] row_mask:0xf bank_mask:0xf bound_ctrl:1
	v_add_f32_dpp v251, v251, v251 quad_perm:[2,3,0,1] row_mask:0xf bank_mask:0xf bound_ctrl:1
	v_add_f32_dpp v252, v252, v252 quad_perm:[2,3,0,1] row_mask:0xf bank_mask:0xf bound_ctrl:1
	v_add_f32_dpp v253, v253, v253 quad_perm:[2,3,0,1] row_mask:0xf bank_mask:0xf bound_ctrl:1
	v_pk_fma_f32 v[6:7], v[240:241], v[234:235], v[6:7] op_sel:[0,1,0]
	v_pk_fma_f32 v[8:9], v[240:241], v[236:237], v[8:9] op_sel_hi:[1,0,1]
	v_add_f32_dpp v250, v250, v250 row_half_mirror row_mask:0xf bank_mask:0xf bound_ctrl:1
	v_add_f32_dpp v251, v251, v251 row_half_mirror row_mask:0xf bank_mask:0xf bound_ctrl:1
	v_add_f32_dpp v252, v252, v252 row_half_mirror row_mask:0xf bank_mask:0xf bound_ctrl:1
	v_add_f32_dpp v253, v253, v253 row_half_mirror row_mask:0xf bank_mask:0xf bound_ctrl:1
	v_pk_fma_f32 v[10:11], v[240:241], v[236:237], v[10:11] op_sel:[0,1,0]
	v_pk_fma_f32 v[12:13], v[240:241], v[238:239], v[12:13] op_sel_hi:[1,0,1]
	v_pk_fma_f32 v[14:15], v[240:241], v[238:239], v[14:15] op_sel:[0,1,0]
	v_pk_fma_f32 v[0:1], v[250:251], v[224:225], v[0:1] op_sel_hi:[1,0,1]
	v_pk_fma_f32 v[2:3], v[250:251], v[224:225], v[2:3] op_sel:[0,1,0]
	v_pk_fma_f32 v[4:5], v[250:251], v[226:227], v[4:5] op_sel_hi:[1,0,1]
	v_pk_fma_f32 v[6:7], v[250:251], v[226:227], v[6:7] op_sel:[0,1,0]
	v_pk_fma_f32 v[8:9], v[250:251], v[228:229], v[8:9] op_sel_hi:[1,0,1]
	v_pk_fma_f32 v[10:11], v[250:251], v[228:229], v[10:11] op_sel:[0,1,0]
	v_pk_fma_f32 v[12:13], v[250:251], v[230:231], v[12:13] op_sel_hi:[1,0,1]
	v_pk_fma_f32 v[14:15], v[250:251], v[230:231], v[14:15] op_sel:[0,1,0]
	v_pk_fma_f32 v[248:249], v[250:251], v[242:243], v[252:253] op_sel_hi:[1,0,1]
	v_pk_fma_f32 v[248:249], v[240:241], v[242:243], v[248:249] op_sel:[0,1,0]
	s_mov_b64 exec, s[98:99]
	ds_write_b64 v201, v[248:249] offset:49152
	s_mov_b64 exec, -1
	s_waitcnt lgkmcnt(1)
; __device__ __forceinline__ void phase_scan(const Params& p, int bid, int nblk, int wv) {
;     ...
;           for (int jj = 0; jj < 8; ++jj) {
;             const int s = sb * 8 + jj;
;             const int sn = (s + 1) & 31;
;             const float* qn = q + sn * 64;
;             f32x2 sa0 = S0[0] * kkn0.lo, sa1 = S1[0] * kkn0.lo, yp0 = S0[0] * wr0.lo, yp1 = S1[0] * wr0.lo;
;             sa0 += S0[1] * kkn0.hi; sa1 += S1[1] * kkn0.hi; yp0 += S0[1] * wr0.hi; yp1 += S1[1] * wr0.hi;
;             sa0 += S0[2] * kkn1.lo; sa1 += S1[2] * kkn1.lo; yp0 += S0[2] * wr1.lo; yp1 += S1[2] * wr1.lo;
;             sa0 += S0[3] * kkn1.hi; sa1 += S1[3] * kkn1.hi; yp0 += S0[3] * wr1.hi; yp1 += S1[3] * wr1.hi;
;             kkn0 = *reinterpret_cast<const f32x4*>(qn); kkn1 = *reinterpret_cast<const f32x4*>(qn + 4);
;             wr0 = *reinterpret_cast<const f32x4*>(qn + 2048); wr1 = *reinterpret_cast<const f32x4*>(qn + 2048 + 4);
;             float a0 = reduce8_np(sa0.x + sa0.y), p0 = reduce8_np(yp0.x + yp0.y);
;             float a1 = reduce8_np(sa1.x + sa1.y), p1 = reduce8_np(yp1.x + yp1.y);
;             f32x2 av0 = {a0, a0}, av1 = {a1, a1}, vv0 = {vv.x, vv.x}, vv1 = {vv.y, vv.y};
;             S0[0] += vv0 * kp0.lo; S0[1] += vv0 * kp0.hi; S0[2] += vv0 * kp1.lo; S0[3] += vv0 * kp1.hi;
;             S1[0] += vv1 * kp0.lo; S1[1] += vv1 * kp0.hi; S1[2] += vv1 * kp1.lo; S1[3] += vv1 * kp1.hi;
;             S0[0] += av0 * ka0.lo; S0[1] += av0 * ka0.hi; S0[2] += av0 * ka1.lo; S0[3] += av0 * ka1.hi;
;             S1[0] += av1 * ka0.lo; S1[1] += av1 * ka0.hi; S1[2] += av1 * ka1.lo; S1[3] += av1 * ka1.hi;
;             float y0 = p0 + a0 * cc.x + vv.x * cc.y;
;             float y1 = p1 + a1 * cc.x + vv.y * cc.y;
;             ka0 = *reinterpret_cast<const f32x4*>(qn + 6144); ka1 = *reinterpret_cast<const f32x4*>(qn + 6144 + 4);
;             kp0 = *reinterpret_cast<const f32x4*>(qn + 8192); kp1 = *reinterpret_cast<const f32x4*>(qn + 8192 + 4);
;             vv = *reinterpret_cast<const f32x2*>(B + 10240 + sn * 64 + row0);
;             cc = *reinterpret_cast<const f32x2*>(B + 14336 + sn * 4);
;             yk0 += ym[jj] * y0; yk1 += ym[jj] * y1;
	ds_read_b128 v[208:211], v200 offset:512
	ds_read_b128 v[212:215], v200 offset:528
	ds_read_b128 v[216:219], v200 offset:8704
	ds_read_b128 v[220:223], v200 offset:8720
	ds_read_b128 v[224:227], v200 offset:25088
	ds_read_b128 v[228:231], v200 offset:25104
	ds_read_b128 v[232:235], v200 offset:33280
	ds_read_b128 v[236:239], v200 offset:33296
	ds_read_b64 v[240:241], v201 offset:41472
	ds_read_b64 v[242:243], v202 offset:57376
	v_pk_mul_f32 v[250:251], v[0:1], v[56:57] op_sel_hi:[1,0]
	v_pk_mul_f32 v[252:253], v[0:1], v[64:65] op_sel_hi:[1,0]
	v_pk_fma_f32 v[250:251], v[2:3], v[56:57], v[250:251] op_sel:[0,1,0]
	v_pk_fma_f32 v[252:253], v[2:3], v[64:65], v[252:253] op_sel:[0,1,0]
	v_pk_fma_f32 v[250:251], v[4:5], v[58:59], v[250:251] op_sel_hi:[1,0,1]
	v_pk_fma_f32 v[252:253], v[4:5], v[66:67], v[252:253] op_sel_hi:[1,0,1]
	v_pk_fma_f32 v[250:251], v[6:7], v[58:59], v[250:251] op_sel:[0,1,0]
	v_pk_fma_f32 v[252:253], v[6:7], v[66:67], v[252:253] op_sel:[0,1,0]
	v_pk_fma_f32 v[250:251], v[8:9], v[60:61], v[250:251] op_sel_hi:[1,0,1]
	v_pk_fma_f32 v[252:253], v[8:9], v[68:69], v[252:253] op_sel_hi:[1,0,1]
	v_pk_fma_f32 v[250:251], v[10:11], v[60:61], v[250:251] op_sel:[0,1,0]
	v_pk_fma_f32 v[252:253], v[10:11], v[68:69], v[252:253] op_sel:[0,1,0]
	v_pk_fma_f32 v[250:251], v[12:13], v[62:63], v[250:251] op_sel_hi:[1,0,1]
	v_pk_fma_f32 v[252:253], v[12:13], v[70:71], v[252:253] op_sel_hi:[1,0,1]
	v_pk_fma_f32 v[250:251], v[14:15], v[62:63], v[250:251] op_sel:[0,1,0]
	v_pk_fma_f32 v[252:253], v[14:15], v[70:71], v[252:253] op_sel:[0,1,0]
	v_pk_fma_f32 v[0:1], v[244:245], v[80:81], v[0:1] op_sel_hi:[1,0,1]
	v_add_f32_dpp v250, v250, v250 quad_perm:[1,0,3,2] row_mask:0xf bank_mask:0xf bound_ctrl:1
	v_add_f32_dpp v251, v251, v251 quad_perm:[1,0,3,2] row_mask:0xf bank_mask:0xf bound_ctrl:1
	v_add_f32_dpp v252, v252, v252 quad_perm:[1,0,3,2] row_mask:0xf bank_mask:0xf bound_ctrl:1
	v_add_f32_dpp v253, v253, v253 quad_perm:[1,0,3,2] row_mask:0xf bank_mask:0xf bound_ctrl:1
	v_pk_fma_f32 v[2:3], v[244:245], v[80:81], v[2:3] op_sel:[0,1,0]
	v_pk_fma_f32 v[4:5], v[244:245], v[82:83], v[4:5] op_sel_hi:[1,0,1]
	v_add_f32_dpp v250, v250, v250 quad_perm:[2,3,0,1] row_mask:0xf bank_mask:0xf bound_ctrl:1
	v_add_f32_dpp v251, v251, v251 quad_perm:[2,3,0,1] row_mask:0xf bank_mask:0xf bound_ctrl:1
	v_add_f32_dpp v252, v252, v252 quad_perm:[2,3,0,1] row_mask:0xf bank_mask:0xf bound_ctrl:1
	v_add_f32_dpp v253, v253, v253 quad_perm:[2,3,0,1] row_mask:0xf bank_mask:0xf bound_ctrl:1
	v_pk_fma_f32 v[6:7], v[244:245], v[82:83], v[6:7] op_sel:[0,1,0]
	v_pk_fma_f32 v[8:9], v[244:245], v[84:85], v[8:9] op_sel_hi:[1,0,1]
	v_add_f32_dpp v250, v250, v250 row_half_mirror row_mask:0xf bank_mask:0xf bound_ctrl:1
	v_add_f32_dpp v251, v251, v251 row_half_mirror row_mask:0xf bank_mask:0xf bound_ctrl:1
	v_add_f32_dpp v252, v252, v252 row_half_mirror row_mask:0xf bank_mask:0xf bound_ctrl:1
	v_add_f32_dpp v253, v253, v253 row_half_mirror row_mask:0xf bank_mask:0xf bound_ctrl:1
	v_pk_fma_f32 v[10:11], v[244:245], v[84:85], v[10:11] op_sel:[0,1,0]
	v_pk_fma_f32 v[12:13], v[244:245], v[86:87], v[12:13] op_sel_hi:[1,0,1]
	v_pk_fma_f32 v[14:15], v[244:245], v[86:87], v[14:15] op_sel:[0,1,0]
	v_pk_fma_f32 v[0:1], v[250:251], v[72:73], v[0:1] op_sel_hi:[1,0,1]
	v_pk_fma_f32 v[2:3], v[250:251], v[72:73], v[2:3] op_sel:[0,1,0]
	v_pk_fma_f32 v[4:5], v[250:251], v[74:75], v[4:5] op_sel_hi:[1,0,1]
	v_pk_fma_f32 v[6:7], v[250:251], v[74:75], v[6:7] op_sel:[0,1,0]
	v_pk_fma_f32 v[8:9], v[250:251], v[76:77], v[8:9] op_sel_hi:[1,0,1]
	v_pk_fma_f32 v[10:11], v[250:251], v[76:77], v[10:11] op_sel:[0,1,0]
	v_pk_fma_f32 v[12:13], v[250:251], v[78:79], v[12:13] op_sel_hi:[1,0,1]
	v_pk_fma_f32 v[14:15], v[250:251], v[78:79], v[14:15] op_sel:[0,1,0]
	v_pk_fma_f32 v[248:249], v[250:251], v[246:247], v[252:253] op_sel_hi:[1,0,1]
	v_pk_fma_f32 v[248:249], v[244:245], v[246:247], v[248:249] op_sel:[0,1,0]
	s_mov_b64 exec, s[98:99]
	ds_write_b64 v201, v[248:249] offset:49408
	s_mov_b64 exec, -1
	s_waitcnt lgkmcnt(1)
	ds_read_b128 v[56:59], v200 offset:768
	ds_read_b128 v[60:63], v200 offset:784
	ds_read_b128 v[64:67], v200 offset:8960
	ds_read_b128 v[68:71], v200 offset:8976
	ds_read_b128 v[72:75], v200 offset:25344
	ds_read_b128 v[76:79], v200 offset:25360
	ds_read_b128 v[80:83], v200 offset:33536
	ds_read_b128 v[84:87], v200 offset:33552
	ds_read_b64 v[244:245], v201 offset:41728
	ds_read_b64 v[246:247], v202 offset:57392
	v_pk_mul_f32 v[250:251], v[0:1], v[208:209] op_sel_hi:[1,0]
	v_pk_mul_f32 v[252:253], v[0:1], v[216:217] op_sel_hi:[1,0]
	v_pk_fma_f32 v[250:251], v[2:3], v[208:209], v[250:251] op_sel:[0,1,0]
	v_pk_fma_f32 v[252:253], v[2:3], v[216:217], v[252:253] op_sel:[0,1,0]
	v_pk_fma_f32 v[250:251], v[4:5], v[210:211], v[250:251] op_sel_hi:[1,0,1]
	v_pk_fma_f32 v[252:253], v[4:5], v[218:219], v[252:253] op_sel_hi:[1,0,1]
	v_pk_fma_f32 v[250:251], v[6:7], v[210:211], v[250:251] op_sel:[0,1,0]
	v_pk_fma_f32 v[252:253], v[6:7], v[218:219], v[252:253] op_sel:[0,1,0]
	v_pk_fma_f32 v[250:251], v[8:9], v[212:213], v[250:251] op_sel_hi:[1,0,1]
	v_pk_fma_f32 v[252:253], v[8:9], v[220:221], v[252:253] op_sel_hi:[1,0,1]
	v_pk_fma_f32 v[250:251], v[10:11], v[212:213], v[250:251] op_sel:[0,1,0]
	v_pk_fma_f32 v[252:253], v[10:11], v[220:221], v[252:253] op_sel:[0,1,0]
	v_pk_fma_f32 v[250:251], v[12:13], v[214:215], v[250:251] op_sel_hi:[1,0,1]
	v_pk_fma_f32 v[252:253], v[12:13], v[222:223], v[252:253] op_sel_hi:[1,0,1]
	v_pk_fma_f32 v[250:251], v[14:15], v[214:215], v[250:251] op_sel:[0,1,0]
	v_pk_fma_f32 v[252:253], v[14:15], v[222:223], v[252:253] op_sel:[0,1,0]
	v_pk_fma_f32 v[0:1], v[240:241], v[232:233], v[0:1] op_sel_hi:[1,0,1]
; __device__ __forceinline__ void phase_scan(const Params& p, int bid, int nblk, int wv) {
;     ...
;           for (int jj = 0; jj < 8; ++jj) {
;             const int s = sb * 8 + jj;
;             const int sn = (s + 1) & 31;
;             const float* qn = q + sn * 64;
;             f32x2 sa0 = S0[0] * kkn0.lo, sa1 = S1[0] * kkn0.lo, yp0 = S0[0] * wr0.lo, yp1 = S1[0] * wr0.lo;
;             sa0 += S0[1] * kkn0.hi; sa1 += S1[1] * kkn0.hi; yp0 += S0[1] * wr0.hi; yp1 += S1[1] * wr0.hi;
;             sa0 += S0[2] * kkn1.lo; sa1 += S1[2] * kkn1.lo; yp0 += S0[2] * wr1.lo; yp1 += S1[2] * wr1.lo;
;             sa0 += S0[3] * kkn1.hi; sa1 += S1[3] * kkn1.hi; yp0 += S0[3] * wr1.hi; yp1 += S1[3] * wr1.hi;
;             kkn0 = *reinterpret_cast<const f32x4*>(qn); kkn1 = *reinterpret_cast<const f32x4*>(qn + 4);
;             wr0 = *reinterpret_cast<const f32x4*>(qn + 2048); wr1 = *reinterpret_cast<const f32x4*>(qn + 2048 + 4);
;             float a0 = reduce8_np(sa0.x + sa0.y), p0 = reduce8_np(yp0.x + yp0.y);
;             float a1 = reduce8_np(sa1.x + sa1.y), p1 = reduce8_np(yp1.x + yp1.y);
;             f32x2 av0 = {a0, a0}, av1 = {a1, a1}, vv0 = {vv.x, vv.x}, vv1 = {vv.y, vv.y};
;             S0[0] += vv0 * kp0.lo; S0[1] += vv0 * kp0.hi; S0[2] += vv0 * kp1.lo; S0[3] += vv0 * kp1.hi;
;             S1[0] += vv1 * kp0.lo; S1[1] += vv1 * kp0.hi; S1[2] += vv1 * kp1.lo; S1[3] += vv1 * kp1.hi;
;             S0[0] += av0 * ka0.lo; S0[1] += av0 * ka0.hi; S0[2] += av0 * ka1.lo; S0[3] += av0 * ka1.hi;
;             S1[0] += av1 * ka0.lo; S1[1] += av1 * ka0.hi; S1[2] += av1 * ka1.lo; S1[3] += av1 * ka1.hi;
;             float y0 = p0 + a0 * cc.x + vv.x * cc.y;
;             float y1 = p1 + a1 * cc.x + vv.y * cc.y;
;             ka0 = *reinterpret_cast<const f32x4*>(qn + 6144); ka1 = *reinterpret_cast<const f32x4*>(qn + 6144 + 4);
;             kp0 = *reinterpret_cast<const f32x4*>(qn + 8192); kp1 = *reinterpret_cast<const f32x4*>(qn + 8192 + 4);
;             vv = *reinterpret_cast<const f32x2*>(B + 10240 + sn * 64 + row0);
;             cc = *reinterpret_cast<const f32x2*>(B + 14336 + sn * 4);
;             yk0 += ym[jj] * y0; yk1 += ym[jj] * y1;
	v_add_f32_dpp v250, v250, v250 quad_perm:[1,0,3,2] row_mask:0xf bank_mask:0xf bound_ctrl:1
	v_add_f32_dpp v251, v251, v251 quad_perm:[1,0,3,2] row_mask:0xf bank_mask:0xf bound_ctrl:1
	v_add_f32_dpp v252, v252, v252 quad_perm:[1,0,3,2] row_mask:0xf bank_mask:0xf bound_ctrl:1
	v_add_f32_dpp v253, v253, v253 quad_perm:[1,0,3,2] row_mask:0xf bank_mask:0xf bound_ctrl:1
	v_pk_fma_f32 v[2:3], v[240:241], v[232:233], v[2:3] op_sel:[0,1,0]
	v_pk_fma_f32 v[4:5], v[240:241], v[234:235], v[4:5] op_sel_hi:[1,0,1]
	v_add_f32_dpp v250, v250, v250 quad_perm:[2,3,0,1] row_mask:0xf bank_mask:0xf bound_ctrl:1
	v_add_f32_dpp v251, v251, v251 quad_perm:[2,3,0,1] row_mask:0xf bank_mask:0xf bound_ctrl:1
	v_add_f32_dpp v252, v252, v252 quad_perm:[2,3,0,1] row_mask:0xf bank_mask:0xf bound_ctrl:1
	v_add_f32_dpp v253, v253, v253 quad_perm:[2,3,0,1] row_mask:0xf bank_mask:0xf bound_ctrl:1
	v_pk_fma_f32 v[6:7], v[240:241], v[234:235], v[6:7] op_sel:[0,1,0]
	v_pk_fma_f32 v[8:9], v[240:241], v[236:237], v[8:9] op_sel_hi:[1,0,1]
	v_add_f32_dpp v250, v250, v250 row_half_mirror row_mask:0xf bank_mask:0xf bound_ctrl:1
	v_add_f32_dpp v251, v251, v251 row_half_mirror row_mask:0xf bank_mask:0xf bound_ctrl:1
	v_add_f32_dpp v252, v252, v252 row_half_mirror row_mask:0xf bank_mask:0xf bound_ctrl:1
	v_add_f32_dpp v253, v253, v253 row_half_mirror row_mask:0xf bank_mask:0xf bound_ctrl:1
	v_pk_fma_f32 v[10:11], v[240:241], v[236:237], v[10:11] op_sel:[0,1,0]
	v_pk_fma_f32 v[12:13], v[240:241], v[238:239], v[12:13] op_sel_hi:[1,0,1]
	v_pk_fma_f32 v[14:15], v[240:241], v[238:239], v[14:15] op_sel:[0,1,0]
	v_pk_fma_f32 v[0:1], v[250:251], v[224:225], v[0:1] op_sel_hi:[1,0,1]
	v_pk_fma_f32 v[2:3], v[250:251], v[224:225], v[2:3] op_sel:[0,1,0]
	v_pk_fma_f32 v[4:5], v[250:251], v[226:227], v[4:5] op_sel_hi:[1,0,1]
	v_pk_fma_f32 v[6:7], v[250:251], v[226:227], v[6:7] op_sel:[0,1,0]
	v_pk_fma_f32 v[8:9], v[250:251], v[228:229], v[8:9] op_sel_hi:[1,0,1]
	v_pk_fma_f32 v[10:11], v[250:251], v[228:229], v[10:11] op_sel:[0,1,0]
	v_pk_fma_f32 v[12:13], v[250:251], v[230:231], v[12:13] op_sel_hi:[1,0,1]
	v_pk_fma_f32 v[14:15], v[250:251], v[230:231], v[14:15] op_sel:[0,1,0]
	v_pk_fma_f32 v[248:249], v[250:251], v[242:243], v[252:253] op_sel_hi:[1,0,1]
	v_pk_fma_f32 v[248:249], v[240:241], v[242:243], v[248:249] op_sel:[0,1,0]
	s_mov_b64 exec, s[98:99]
	ds_write_b64 v201, v[248:249] offset:49664
	s_mov_b64 exec, -1
	s_waitcnt lgkmcnt(1)
	ds_read_b128 v[208:211], v200 offset:1024
	ds_read_b128 v[212:215], v200 offset:1040
	ds_read_b128 v[216:219], v200 offset:9216
	ds_read_b128 v[220:223], v200 offset:9232
	ds_read_b128 v[224:227], v200 offset:25600
	ds_read_b128 v[228:231], v200 offset:25616
	ds_read_b128 v[232:235], v200 offset:33792
	ds_read_b128 v[236:239], v200 offset:33808
	ds_read_b64 v[240:241], v201 offset:41984
	ds_read_b64 v[242:243], v202 offset:57408
	v_pk_mul_f32 v[250:251], v[0:1], v[56:57] op_sel_hi:[1,0]
	v_pk_mul_f32 v[252:253], v[0:1], v[64:65] op_sel_hi:[1,0]
	v_pk_fma_f32 v[250:251], v[2:3], v[56:57], v[250:251] op_sel:[0,1,0]
	v_pk_fma_f32 v[252:253], v[2:3], v[64:65], v[252:253] op_sel:[0,1,0]
	v_pk_fma_f32 v[250:251], v[4:5], v[58:59], v[250:251] op_sel_hi:[1,0,1]
	v_pk_fma_f32 v[252:253], v[4:5], v[66:67], v[252:253] op_sel_hi:[1,0,1]
	v_pk_fma_f32 v[250:251], v[6:7], v[58:59], v[250:251] op_sel:[0,1,0]
	v_pk_fma_f32 v[252:253], v[6:7], v[66:67], v[252:253] op_sel:[0,1,0]
	v_pk_fma_f32 v[250:251], v[8:9], v[60:61], v[250:251] op_sel_hi:[1,0,1]
	v_pk_fma_f32 v[252:253], v[8:9], v[68:69], v[252:253] op_sel_hi:[1,0,1]
	v_pk_fma_f32 v[250:251], v[10:11], v[60:61], v[250:251] op_sel:[0,1,0]
	v_pk_fma_f32 v[252:253], v[10:11], v[68:69], v[252:253] op_sel:[0,1,0]
	v_pk_fma_f32 v[250:251], v[12:13], v[62:63], v[250:251] op_sel_hi:[1,0,1]
	v_pk_fma_f32 v[252:253], v[12:13], v[70:71], v[252:253] op_sel_hi:[1,0,1]
	v_pk_fma_f32 v[250:251], v[14:15], v[62:63], v[250:251] op_sel:[0,1,0]
	v_pk_fma_f32 v[252:253], v[14:15], v[70:71], v[252:253] op_sel:[0,1,0]
	v_pk_fma_f32 v[0:1], v[244:245], v[80:81], v[0:1] op_sel_hi:[1,0,1]
	v_add_f32_dpp v250, v250, v250 quad_perm:[1,0,3,2] row_mask:0xf bank_mask:0xf bound_ctrl:1
	v_add_f32_dpp v251, v251, v251 quad_perm:[1,0,3,2] row_mask:0xf bank_mask:0xf bound_ctrl:1
	v_add_f32_dpp v252, v252, v252 quad_perm:[1,0,3,2] row_mask:0xf bank_mask:0xf bound_ctrl:1
	v_add_f32_dpp v253, v253, v253 quad_perm:[1,0,3,2] row_mask:0xf bank_mask:0xf bound_ctrl:1
	v_pk_fma_f32 v[2:3], v[244:245], v[80:81], v[2:3] op_sel:[0,1,0]
	v_pk_fma_f32 v[4:5], v[244:245], v[82:83], v[4:5] op_sel_hi:[1,0,1]
	v_add_f32_dpp v250, v250, v250 quad_perm:[2,3,0,1] row_mask:0xf bank_mask:0xf bound_ctrl:1
	v_add_f32_dpp v251, v251, v251 quad_perm:[2,3,0,1] row_mask:0xf bank_mask:0xf bound_ctrl:1
	v_add_f32_dpp v252, v252, v252 quad_perm:[2,3,0,1] row_mask:0xf bank_mask:0xf bound_ctrl:1
	v_add_f32_dpp v253, v253, v253 quad_perm:[2,3,0,1] row_mask:0xf bank_mask:0xf bound_ctrl:1
	v_pk_fma_f32 v[6:7], v[244:245], v[82:83], v[6:7] op_sel:[0,1,0]
	v_pk_fma_f32 v[8:9], v[244:245], v[84:85], v[8:9] op_sel_hi:[1,0,1]
	v_add_f32_dpp v250, v250, v250 row_half_mirror row_mask:0xf bank_mask:0xf bound_ctrl:1
	v_add_f32_dpp v251, v251, v251 row_half_mirror row_mask:0xf bank_mask:0xf bound_ctrl:1
	v_add_f32_dpp v252, v252, v252 row_half_mirror row_mask:0xf bank_mask:0xf bound_ctrl:1
	v_add_f32_dpp v253, v253, v253 row_half_mirror row_mask:0xf bank_mask:0xf bound_ctrl:1
	v_pk_fma_f32 v[10:11], v[244:245], v[84:85], v[10:11] op_sel:[0,1,0]
	v_pk_fma_f32 v[12:13], v[244:245], v[86:87], v[12:13] op_sel_hi:[1,0,1]
	v_pk_fma_f32 v[14:15], v[244:245], v[86:87], v[14:15] op_sel:[0,1,0]
	v_pk_fma_f32 v[0:1], v[250:251], v[72:73], v[0:1] op_sel_hi:[1,0,1]
	v_pk_fma_f32 v[2:3], v[250:251], v[72:73], v[2:3] op_sel:[0,1,0]
	v_pk_fma_f32 v[4:5], v[250:251], v[74:75], v[4:5] op_sel_hi:[1,0,1]
	v_pk_fma_f32 v[6:7], v[250:251], v[74:75], v[6:7] op_sel:[0,1,0]
	v_pk_fma_f32 v[8:9], v[250:251], v[76:77], v[8:9] op_sel_hi:[1,0,1]
	v_pk_fma_f32 v[10:11], v[250:251], v[76:77], v[10:11] op_sel:[0,1,0]
	v_pk_fma_f32 v[12:13], v[250:251], v[78:79], v[12:13] op_sel_hi:[1,0,1]
	v_pk_fma_f32 v[14:15], v[250:251], v[78:79], v[14:15] op_sel:[0,1,0]
	v_pk_fma_f32 v[248:249], v[250:251], v[246:247], v[252:253] op_sel_hi:[1,0,1]
	v_pk_fma_f32 v[248:249], v[244:245], v[246:247], v[248:249] op_sel:[0,1,0]
	s_mov_b64 exec, s[98:99]
	ds_write_b64 v201, v[248:249] offset:49920
	s_mov_b64 exec, -1
	s_waitcnt lgkmcnt(1)
; __device__ __forceinline__ void phase_scan(const Params& p, int bid, int nblk, int wv) {
;     ...
;           for (int jj = 0; jj < 8; ++jj) {
;             const int s = sb * 8 + jj;
;             const int sn = (s + 1) & 31;
;             const float* qn = q + sn * 64;
;             f32x2 sa0 = S0[0] * kkn0.lo, sa1 = S1[0] * kkn0.lo, yp0 = S0[0] * wr0.lo, yp1 = S1[0] * wr0.lo;
;             sa0 += S0[1] * kkn0.hi; sa1 += S1[1] * kkn0.hi; yp0 += S0[1] * wr0.hi; yp1 += S1[1] * wr0.hi;
;             sa0 += S0[2] * kkn1.lo; sa1 += S1[2] * kkn1.lo; yp0 += S0[2] * wr1.lo; yp1 += S1[2] * wr1.lo;
;             sa0 += S0[3] * kkn1.hi; sa1 += S1[3] * kkn1.hi; yp0 += S0[3] * wr1.hi; yp1 += S1[3] * wr1.hi;
;             kkn0 = *reinterpret_cast<const f32x4*>(qn); kkn1 = *reinterpret_cast<const f32x4*>(qn + 4);
;             wr0 = *reinterpret_cast<const f32x4*>(qn + 2048); wr1 = *reinterpret_cast<const f32x4*>(qn + 2048 + 4);
;             float a0 = reduce8_np(sa0.x + sa0.y), p0 = reduce8_np(yp0.x + yp0.y);
;             float a1 = reduce8_np(sa1.x + sa1.y), p1 = reduce8_np(yp1.x + yp1.y);
;             f32x2 av0 = {a0, a0}, av1 = {a1, a1}, vv0 = {vv.x, vv.x}, vv1 = {vv.y, vv.y};
;             S0[0] += vv0 * kp0.lo; S0[1] += vv0 * kp0.hi; S0[2] += vv0 * kp1.lo; S0[3] += vv0 * kp1.hi;
;             S1[0] += vv1 * kp0.lo; S1[1] += vv1 * kp0.hi; S1[2] += vv1 * kp1.lo; S1[3] += vv1 * kp1.hi;
;             S0[0] += av0 * ka0.lo; S0[1] += av0 * ka0.hi; S0[2] += av0 * ka1.lo; S0[3] += av0 * ka1.hi;
;             S1[0] += av1 * ka0.lo; S1[1] += av1 * ka0.hi; S1[2] += av1 * ka1.lo; S1[3] += av1 * ka1.hi;
;             float y0 = p0 + a0 * cc.x + vv.x * cc.y;
;             float y1 = p1 + a1 * cc.x + vv.y * cc.y;
;             ka0 = *reinterpret_cast<const f32x4*>(qn + 6144); ka1 = *reinterpret_cast<const f32x4*>(qn + 6144 + 4);
;             kp0 = *reinterpret_cast<const f32x4*>(qn + 8192); kp1 = *reinterpret_cast<const f32x4*>(qn + 8192 + 4);
;             vv = *reinterpret_cast<const f32x2*>(B + 10240 + sn * 64 + row0);
;             cc = *reinterpret_cast<const f32x2*>(B + 14336 + sn * 4);
;             yk0 += ym[jj] * y0; yk1 += ym[jj] * y1;
	ds_read_b128 v[56:59], v200 offset:1280
	ds_read_b128 v[60:63], v200 offset:1296
	ds_read_b128 v[64:67], v200 offset:9472
	ds_read_b128 v[68:71], v200 offset:9488
	ds_read_b128 v[72:75], v200 offset:25856
	ds_read_b128 v[76:79], v200 offset:25872
	ds_read_b128 v[80:83], v200 offset:34048
	ds_read_b128 v[84:87], v200 offset:34064
	ds_read_b64 v[244:245], v201 offset:42240
	ds_read_b64 v[246:247], v202 offset:57424
	v_pk_mul_f32 v[250:251], v[0:1], v[208:209] op_sel_hi:[1,0]
	v_pk_mul_f32 v[252:253], v[0:1], v[216:217] op_sel_hi:[1,0]
	v_pk_fma_f32 v[250:251], v[2:3], v[208:209], v[250:251] op_sel:[0,1,0]
	v_pk_fma_f32 v[252:253], v[2:3], v[216:217], v[252:253] op_sel:[0,1,0]
	v_pk_fma_f32 v[250:251], v[4:5], v[210:211], v[250:251] op_sel_hi:[1,0,1]
	v_pk_fma_f32 v[252:253], v[4:5], v[218:219], v[252:253] op_sel_hi:[1,0,1]
	v_pk_fma_f32 v[250:251], v[6:7], v[210:211], v[250:251] op_sel:[0,1,0]
	v_pk_fma_f32 v[252:253], v[6:7], v[218:219], v[252:253] op_sel:[0,1,0]
	v_pk_fma_f32 v[250:251], v[8:9], v[212:213], v[250:251] op_sel_hi:[1,0,1]
	v_pk_fma_f32 v[252:253], v[8:9], v[220:221], v[252:253] op_sel_hi:[1,0,1]
	v_pk_fma_f32 v[250:251], v[10:11], v[212:213], v[250:251] op_sel:[0,1,0]
	v_pk_fma_f32 v[252:253], v[10:11], v[220:221], v[252:253] op_sel:[0,1,0]
	v_pk_fma_f32 v[250:251], v[12:13], v[214:215], v[250:251] op_sel_hi:[1,0,1]
	v_pk_fma_f32 v[252:253], v[12:13], v[222:223], v[252:253] op_sel_hi:[1,0,1]
	v_pk_fma_f32 v[250:251], v[14:15], v[214:215], v[250:251] op_sel:[0,1,0]
	v_pk_fma_f32 v[252:253], v[14:15], v[222:223], v[252:253] op_sel:[0,1,0]
	v_pk_fma_f32 v[0:1], v[240:241], v[232:233], v[0:1] op_sel_hi:[1,0,1]
	v_add_f32_dpp v250, v250, v250 quad_perm:[1,0,3,2] row_mask:0xf bank_mask:0xf bound_ctrl:1
	v_add_f32_dpp v251, v251, v251 quad_perm:[1,0,3,2] row_mask:0xf bank_mask:0xf bound_ctrl:1
	v_add_f32_dpp v252, v252, v252 quad_perm:[1,0,3,2] row_mask:0xf bank_mask:0xf bound_ctrl:1
	v_add_f32_dpp v253, v253, v253 quad_perm:[1,0,3,2] row_mask:0xf bank_mask:0xf bound_ctrl:1
	v_pk_fma_f32 v[2:3], v[240:241], v[232:233], v[2:3] op_sel:[0,1,0]
	v_pk_fma_f32 v[4:5], v[240:241], v[234:235], v[4:5] op_sel_hi:[1,0,1]
	v_add_f32_dpp v250, v250, v250 quad_perm:[2,3,0,1] row_mask:0xf bank_mask:0xf bound_ctrl:1
	v_add_f32_dpp v251, v251, v251 quad_perm:[2,3,0,1] row_mask:0xf bank_mask:0xf bound_ctrl:1
	v_add_f32_dpp v252, v252, v252 quad_perm:[2,3,0,1] row_mask:0xf bank_mask:0xf bound_ctrl:1
	v_add_f32_dpp v253, v253, v253 quad_perm:[2,3,0,1] row_mask:0xf bank_mask:0xf bound_ctrl:1
	v_pk_fma_f32 v[6:7], v[240:241], v[234:235], v[6:7] op_sel:[0,1,0]
	v_pk_fma_f32 v[8:9], v[240:241], v[236:237], v[8:9] op_sel_hi:[1,0,1]
	v_add_f32_dpp v250, v250, v250 row_half_mirror row_mask:0xf bank_mask:0xf bound_ctrl:1
	v_add_f32_dpp v251, v251, v251 row_half_mirror row_mask:0xf bank_mask:0xf bound_ctrl:1
	v_add_f32_dpp v252, v252, v252 row_half_mirror row_mask:0xf bank_mask:0xf bound_ctrl:1
	v_add_f32_dpp v253, v253, v253 row_half_mirror row_mask:0xf bank_mask:0xf bound_ctrl:1
	v_pk_fma_f32 v[10:11], v[240:241], v[236:237], v[10:11] op_sel:[0,1,0]
	v_pk_fma_f32 v[12:13], v[240:241], v[238:239], v[12:13] op_sel_hi:[1,0,1]
	v_pk_fma_f32 v[14:15], v[240:241], v[238:239], v[14:15] op_sel:[0,1,0]
	v_pk_fma_f32 v[0:1], v[250:251], v[224:225], v[0:1] op_sel_hi:[1,0,1]
	v_pk_fma_f32 v[2:3], v[250:251], v[224:225], v[2:3] op_sel:[0,1,0]
	v_pk_fma_f32 v[4:5], v[250:251], v[226:227], v[4:5] op_sel_hi:[1,0,1]
	v_pk_fma_f32 v[6:7], v[250:251], v[226:227], v[6:7] op_sel:[0,1,0]
	v_pk_fma_f32 v[8:9], v[250:251], v[228:229], v[8:9] op_sel_hi:[1,0,1]
	v_pk_fma_f32 v[10:11], v[250:251], v[228:229], v[10:11] op_sel:[0,1,0]
	v_pk_fma_f32 v[12:13], v[250:251], v[230:231], v[12:13] op_sel_hi:[1,0,1]
	v_pk_fma_f32 v[14:15], v[250:251], v[230:231], v[14:15] op_sel:[0,1,0]
	v_pk_fma_f32 v[248:249], v[250:251], v[242:243], v[252:253] op_sel_hi:[1,0,1]
	v_pk_fma_f32 v[248:249], v[240:241], v[242:243], v[248:249] op_sel:[0,1,0]
	s_mov_b64 exec, s[98:99]
	ds_write_b64 v201, v[248:249] offset:50176
	s_mov_b64 exec, -1
	s_waitcnt lgkmcnt(1)
	ds_read_b128 v[208:211], v200 offset:1536
	ds_read_b128 v[212:215], v200 offset:1552
	ds_read_b128 v[216:219], v200 offset:9728
	ds_read_b128 v[220:223], v200 offset:9744
	ds_read_b128 v[224:227], v200 offset:26112
	ds_read_b128 v[228:231], v200 offset:26128
	ds_read_b128 v[232:235], v200 offset:34304
	ds_read_b128 v[236:239], v200 offset:34320
	ds_read_b64 v[240:241], v201 offset:42496
	ds_read_b64 v[242:243], v202 offset:57440
	v_pk_mul_f32 v[250:251], v[0:1], v[56:57] op_sel_hi:[1,0]
	v_pk_mul_f32 v[252:253], v[0:1], v[64:65] op_sel_hi:[1,0]
	v_pk_fma_f32 v[250:251], v[2:3], v[56:57], v[250:251] op_sel:[0,1,0]
	v_pk_fma_f32 v[252:253], v[2:3], v[64:65], v[252:253] op_sel:[0,1,0]
	v_pk_fma_f32 v[250:251], v[4:5], v[58:59], v[250:251] op_sel_hi:[1,0,1]
	v_pk_fma_f32 v[252:253], v[4:5], v[66:67], v[252:253] op_sel_hi:[1,0,1]
	v_pk_fma_f32 v[250:251], v[6:7], v[58:59], v[250:251] op_sel:[0,1,0]
	v_pk_fma_f32 v[252:253], v[6:7], v[66:67], v[252:253] op_sel:[0,1,0]
	v_pk_fma_f32 v[250:251], v[8:9], v[60:61], v[250:251] op_sel_hi:[1,0,1]
	v_pk_fma_f32 v[252:253], v[8:9], v[68:69], v[252:253] op_sel_hi:[1,0,1]
	v_pk_fma_f32 v[250:251], v[10:11], v[60:61], v[250:251] op_sel:[0,1,0]
	v_pk_fma_f32 v[252:253], v[10:11], v[68:69], v[252:253] op_sel:[0,1,0]
	v_pk_fma_f32 v[250:251], v[12:13], v[62:63], v[250:251] op_sel_hi:[1,0,1]
	v_pk_fma_f32 v[252:253], v[12:13], v[70:71], v[252:253] op_sel_hi:[1,0,1]
	v_pk_fma_f32 v[250:251], v[14:15], v[62:63], v[250:251] op_sel:[0,1,0]
	v_pk_fma_f32 v[252:253], v[14:15], v[70:71], v[252:253] op_sel:[0,1,0]
; __device__ __forceinline__ void phase_scan(const Params& p, int bid, int nblk, int wv) {
;     ...
;           for (int jj = 0; jj < 8; ++jj) {
;             const int s = sb * 8 + jj;
;             const int sn = (s + 1) & 31;
;             const float* qn = q + sn * 64;
;             f32x2 sa0 = S0[0] * kkn0.lo, sa1 = S1[0] * kkn0.lo, yp0 = S0[0] * wr0.lo, yp1 = S1[0] * wr0.lo;
;             sa0 += S0[1] * kkn0.hi; sa1 += S1[1] * kkn0.hi; yp0 += S0[1] * wr0.hi; yp1 += S1[1] * wr0.hi;
;             sa0 += S0[2] * kkn1.lo; sa1 += S1[2] * kkn1.lo; yp0 += S0[2] * wr1.lo; yp1 += S1[2] * wr1.lo;
;             sa0 += S0[3] * kkn1.hi; sa1 += S1[3] * kkn1.hi; yp0 += S0[3] * wr1.hi; yp1 += S1[3] * wr1.hi;
;             kkn0 = *reinterpret_cast<const f32x4*>(qn); kkn1 = *reinterpret_cast<const f32x4*>(qn + 4);
;             wr0 = *reinterpret_cast<const f32x4*>(qn + 2048); wr1 = *reinterpret_cast<const f32x4*>(qn + 2048 + 4);
;             float a0 = reduce8_np(sa0.x + sa0.y), p0 = reduce8_np(yp0.x + yp0.y);
;             float a1 = reduce8_np(sa1.x + sa1.y), p1 = reduce8_np(yp1.x + yp1.y);
;             f32x2 av0 = {a0, a0}, av1 = {a1, a1}, vv0 = {vv.x, vv.x}, vv1 = {vv.y, vv.y};
;             S0[0] += vv0 * kp0.lo; S0[1] += vv0 * kp0.hi; S0[2] += vv0 * kp1.lo; S0[3] += vv0 * kp1.hi;
;             S1[0] += vv1 * kp0.lo; S1[1] += vv1 * kp0.hi; S1[2] += vv1 * kp1.lo; S1[3] += vv1 * kp1.hi;
;             S0[0] += av0 * ka0.lo; S0[1] += av0 * ka0.hi; S0[2] += av0 * ka1.lo; S0[3] += av0 * ka1.hi;
;             S1[0] += av1 * ka0.lo; S1[1] += av1 * ka0.hi; S1[2] += av1 * ka1.lo; S1[3] += av1 * ka1.hi;
;             float y0 = p0 + a0 * cc.x + vv.x * cc.y;
;             float y1 = p1 + a1 * cc.x + vv.y * cc.y;
;             ka0 = *reinterpret_cast<const f32x4*>(qn + 6144); ka1 = *reinterpret_cast<const f32x4*>(qn + 6144 + 4);
;             kp0 = *reinterpret_cast<const f32x4*>(qn + 8192); kp1 = *reinterpret_cast<const f32x4*>(qn + 8192 + 4);
;             vv = *reinterpret_cast<const f32x2*>(B + 10240 + sn * 64 + row0);
;             cc = *reinterpret_cast<const f32x2*>(B + 14336 + sn * 4);
;             yk0 += ym[jj] * y0; yk1 += ym[jj] * y1;
	v_pk_fma_f32 v[0:1], v[244:245], v[80:81], v[0:1] op_sel_hi:[1,0,1]
	v_add_f32_dpp v250, v250, v250 quad_perm:[1,0,3,2] row_mask:0xf bank_mask:0xf bound_ctrl:1
	v_add_f32_dpp v251, v251, v251 quad_perm:[1,0,3,2] row_mask:0xf bank_mask:0xf bound_ctrl:1
	v_add_f32_dpp v252, v252, v252 quad_perm:[1,0,3,2] row_mask:0xf bank_mask:0xf bound_ctrl:1
	v_add_f32_dpp v253, v253, v253 quad_perm:[1,0,3,2] row_mask:0xf bank_mask:0xf bound_ctrl:1
	v_pk_fma_f32 v[2:3], v[244:245], v[80:81], v[2:3] op_sel:[0,1,0]
	v_pk_fma_f32 v[4:5], v[244:245], v[82:83], v[4:5] op_sel_hi:[1,0,1]
	v_add_f32_dpp v250, v250, v250 quad_perm:[2,3,0,1] row_mask:0xf bank_mask:0xf bound_ctrl:1
	v_add_f32_dpp v251, v251, v251 quad_perm:[2,3,0,1] row_mask:0xf bank_mask:0xf bound_ctrl:1
	v_add_f32_dpp v252, v252, v252 quad_perm:[2,3,0,1] row_mask:0xf bank_mask:0xf bound_ctrl:1
	v_add_f32_dpp v253, v253, v253 quad_perm:[2,3,0,1] row_mask:0xf bank_mask:0xf bound_ctrl:1
	v_pk_fma_f32 v[6:7], v[244:245], v[82:83], v[6:7] op_sel:[0,1,0]
	v_pk_fma_f32 v[8:9], v[244:245], v[84:85], v[8:9] op_sel_hi:[1,0,1]
	v_add_f32_dpp v250, v250, v250 row_half_mirror row_mask:0xf bank_mask:0xf bound_ctrl:1
	v_add_f32_dpp v251, v251, v251 row_half_mirror row_mask:0xf bank_mask:0xf bound_ctrl:1
	v_add_f32_dpp v252, v252, v252 row_half_mirror row_mask:0xf bank_mask:0xf bound_ctrl:1
	v_add_f32_dpp v253, v253, v253 row_half_mirror row_mask:0xf bank_mask:0xf bound_ctrl:1
	v_pk_fma_f32 v[10:11], v[244:245], v[84:85], v[10:11] op_sel:[0,1,0]
	v_pk_fma_f32 v[12:13], v[244:245], v[86:87], v[12:13] op_sel_hi:[1,0,1]
	v_pk_fma_f32 v[14:15], v[244:245], v[86:87], v[14:15] op_sel:[0,1,0]
	v_pk_fma_f32 v[0:1], v[250:251], v[72:73], v[0:1] op_sel_hi:[1,0,1]
	v_pk_fma_f32 v[2:3], v[250:251], v[72:73], v[2:3] op_sel:[0,1,0]
	v_pk_fma_f32 v[4:5], v[250:251], v[74:75], v[4:5] op_sel_hi:[1,0,1]
	v_pk_fma_f32 v[6:7], v[250:251], v[74:75], v[6:7] op_sel:[0,1,0]
	v_pk_fma_f32 v[8:9], v[250:251], v[76:77], v[8:9] op_sel_hi:[1,0,1]
	v_pk_fma_f32 v[10:11], v[250:251], v[76:77], v[10:11] op_sel:[0,1,0]
	v_pk_fma_f32 v[12:13], v[250:251], v[78:79], v[12:13] op_sel_hi:[1,0,1]
	v_pk_fma_f32 v[14:15], v[250:251], v[78:79], v[14:15] op_sel:[0,1,0]
	v_pk_fma_f32 v[248:249], v[250:251], v[246:247], v[252:253] op_sel_hi:[1,0,1]
	v_pk_fma_f32 v[248:249], v[244:245], v[246:247], v[248:249] op_sel:[0,1,0]
	s_mov_b64 exec, s[98:99]
	ds_write_b64 v201, v[248:249] offset:50432
	s_mov_b64 exec, -1
	s_waitcnt lgkmcnt(1)
	ds_read_b128 v[56:59], v200 offset:1792
	ds_read_b128 v[60:63], v200 offset:1808
	ds_read_b128 v[64:67], v200 offset:9984
	ds_read_b128 v[68:71], v200 offset:10000
	ds_read_b128 v[72:75], v200 offset:26368
	ds_read_b128 v[76:79], v200 offset:26384
	ds_read_b128 v[80:83], v200 offset:34560
	ds_read_b128 v[84:87], v200 offset:34576
	ds_read_b64 v[244:245], v201 offset:42752
	ds_read_b64 v[246:247], v202 offset:57456
	v_pk_mul_f32 v[250:251], v[0:1], v[208:209] op_sel_hi:[1,0]
	v_pk_mul_f32 v[252:253], v[0:1], v[216:217] op_sel_hi:[1,0]
	v_pk_fma_f32 v[250:251], v[2:3], v[208:209], v[250:251] op_sel:[0,1,0]
	v_pk_fma_f32 v[252:253], v[2:3], v[216:217], v[252:253] op_sel:[0,1,0]
	v_pk_fma_f32 v[250:251], v[4:5], v[210:211], v[250:251] op_sel_hi:[1,0,1]
	v_pk_fma_f32 v[252:253], v[4:5], v[218:219], v[252:253] op_sel_hi:[1,0,1]
	v_pk_fma_f32 v[250:251], v[6:7], v[210:211], v[250:251] op_sel:[0,1,0]
	v_pk_fma_f32 v[252:253], v[6:7], v[218:219], v[252:253] op_sel:[0,1,0]
	v_pk_fma_f32 v[250:251], v[8:9], v[212:213], v[250:251] op_sel_hi:[1,0,1]
	v_pk_fma_f32 v[252:253], v[8:9], v[220:221], v[252:253] op_sel_hi:[1,0,1]
	v_pk_fma_f32 v[250:251], v[10:11], v[212:213], v[250:251] op_sel:[0,1,0]
	v_pk_fma_f32 v[252:253], v[10:11], v[220:221], v[252:253] op_sel:[0,1,0]
	v_pk_fma_f32 v[250:251], v[12:13], v[214:215], v[250:251] op_sel_hi:[1,0,1]
	v_pk_fma_f32 v[252:253], v[12:13], v[222:223], v[252:253] op_sel_hi:[1,0,1]
	v_pk_fma_f32 v[250:251], v[14:15], v[214:215], v[250:251] op_sel:[0,1,0]
	v_pk_fma_f32 v[252:253], v[14:15], v[222:223], v[252:253] op_sel:[0,1,0]
	v_pk_fma_f32 v[0:1], v[240:241], v[232:233], v[0:1] op_sel_hi:[1,0,1]
	v_add_f32_dpp v250, v250, v250 quad_perm:[1,0,3,2] row_mask:0xf bank_mask:0xf bound_ctrl:1
	v_add_f32_dpp v251, v251, v251 quad_perm:[1,0,3,2] row_mask:0xf bank_mask:0xf bound_ctrl:1
	v_add_f32_dpp v252, v252, v252 quad_perm:[1,0,3,2] row_mask:0xf bank_mask:0xf bound_ctrl:1
	v_add_f32_dpp v253, v253, v253 quad_perm:[1,0,3,2] row_mask:0xf bank_mask:0xf bound_ctrl:1
	v_pk_fma_f32 v[2:3], v[240:241], v[232:233], v[2:3] op_sel:[0,1,0]
	v_pk_fma_f32 v[4:5], v[240:241], v[234:235], v[4:5] op_sel_hi:[1,0,1]
	v_add_f32_dpp v250, v250, v250 quad_perm:[2,3,0,1] row_mask:0xf bank_mask:0xf bound_ctrl:1
	v_add_f32_dpp v251, v251, v251 quad_perm:[2,3,0,1] row_mask:0xf bank_mask:0xf bound_ctrl:1
	v_add_f32_dpp v252, v252, v252 quad_perm:[2,3,0,1] row_mask:0xf bank_mask:0xf bound_ctrl:1
	v_add_f32_dpp v253, v253, v253 quad_perm:[2,3,0,1] row_mask:0xf bank_mask:0xf bound_ctrl:1
	v_pk_fma_f32 v[6:7], v[240:241], v[234:235], v[6:7] op_sel:[0,1,0]
	v_pk_fma_f32 v[8:9], v[240:241], v[236:237], v[8:9] op_sel_hi:[1,0,1]
	v_add_f32_dpp v250, v250, v250 row_half_mirror row_mask:0xf bank_mask:0xf bound_ctrl:1
	v_add_f32_dpp v251, v251, v251 row_half_mirror row_mask:0xf bank_mask:0xf bound_ctrl:1
	v_add_f32_dpp v252, v252, v252 row_half_mirror row_mask:0xf bank_mask:0xf bound_ctrl:1
	v_add_f32_dpp v253, v253, v253 row_half_mirror row_mask:0xf bank_mask:0xf bound_ctrl:1
	v_pk_fma_f32 v[10:11], v[240:241], v[236:237], v[10:11] op_sel:[0,1,0]
	v_pk_fma_f32 v[12:13], v[240:241], v[238:239], v[12:13] op_sel_hi:[1,0,1]
	v_pk_fma_f32 v[14:15], v[240:241], v[238:239], v[14:15] op_sel:[0,1,0]
	v_pk_fma_f32 v[0:1], v[250:251], v[224:225], v[0:1] op_sel_hi:[1,0,1]
	v_pk_fma_f32 v[2:3], v[250:251], v[224:225], v[2:3] op_sel:[0,1,0]
	v_pk_fma_f32 v[4:5], v[250:251], v[226:227], v[4:5] op_sel_hi:[1,0,1]
	v_pk_fma_f32 v[6:7], v[250:251], v[226:227], v[6:7] op_sel:[0,1,0]
	v_pk_fma_f32 v[8:9], v[250:251], v[228:229], v[8:9] op_sel_hi:[1,0,1]
	v_pk_fma_f32 v[10:11], v[250:251], v[228:229], v[10:11] op_sel:[0,1,0]
	v_pk_fma_f32 v[12:13], v[250:251], v[230:231], v[12:13] op_sel_hi:[1,0,1]
	v_pk_fma_f32 v[14:15], v[250:251], v[230:231], v[14:15] op_sel:[0,1,0]
	v_pk_fma_f32 v[248:249], v[250:251], v[242:243], v[252:253] op_sel_hi:[1,0,1]
	v_pk_fma_f32 v[248:249], v[240:241], v[242:243], v[248:249] op_sel:[0,1,0]
	s_mov_b64 exec, s[98:99]
	ds_write_b64 v201, v[248:249] offset:50688
	s_mov_b64 exec, -1
	s_waitcnt lgkmcnt(1)
; __device__ __forceinline__ void phase_scan(const Params& p, int bid, int nblk, int wv) {
;     ...
;             ka0 = *reinterpret_cast<const f32x4*>(qn + 6144); ka1 = *reinterpret_cast<const f32x4*>(qn + 6144 + 4);
;             kp0 = *reinterpret_cast<const f32x4*>(qn + 8192); kp1 = *reinterpret_cast<const f32x4*>(qn + 8192 + 4);
;             vv = *reinterpret_cast<const f32x2*>(B + 10240 + sn * 64 + row0);
;             cc = *reinterpret_cast<const f32x2*>(B + 14336 + sn * 4);
;             yk0 += ym[jj] * y0; yk1 += ym[jj] * y1;
;           }
;           *reinterpret_cast<f32x2*>(B + 12288 + (sb * 8 + kq) * 64 + row0) = f32x2{yk0, yk1};
;           {
;             const f32x4 e0 = *reinterpret_cast<const f32x4*>(We + sb * 64), e1 = *reinterpret_cast<const f32x4*>(We + sb * 64 + 4);
;             S0[0] *= e0.lo; S0[1] *= e0.hi; S0[2] *= e1.lo; S0[3] *= e1.hi;
;             S1[0] *= e0.lo; S1[1] *= e0.hi; S1[2] *= e1.lo; S1[3] *= e1.hi;
;           }
;           }
	ds_read_b128 v[208:211], v200 offset:2048
	ds_read_b128 v[212:215], v200 offset:2064
	ds_read_b128 v[216:219], v200 offset:10240
	ds_read_b128 v[220:223], v200 offset:10256
	ds_read_b128 v[224:227], v200 offset:26624
	ds_read_b128 v[228:231], v200 offset:26640
	ds_read_b128 v[232:235], v200 offset:34816
	ds_read_b128 v[236:239], v200 offset:34832
	ds_read_b64 v[240:241], v201 offset:43008
	ds_read_b64 v[242:243], v202 offset:57472
	ds_read_b128 v[16:19], v203
	ds_read_b128 v[20:23], v203 offset:16
	v_pk_mul_f32 v[250:251], v[0:1], v[56:57] op_sel_hi:[1,0]
	v_pk_mul_f32 v[252:253], v[0:1], v[64:65] op_sel_hi:[1,0]
	v_pk_fma_f32 v[250:251], v[2:3], v[56:57], v[250:251] op_sel:[0,1,0]
	v_pk_fma_f32 v[252:253], v[2:3], v[64:65], v[252:253] op_sel:[0,1,0]
	v_pk_fma_f32 v[250:251], v[4:5], v[58:59], v[250:251] op_sel_hi:[1,0,1]
	v_pk_fma_f32 v[252:253], v[4:5], v[66:67], v[252:253] op_sel_hi:[1,0,1]
	v_pk_fma_f32 v[250:251], v[6:7], v[58:59], v[250:251] op_sel:[0,1,0]
	v_pk_fma_f32 v[252:253], v[6:7], v[66:67], v[252:253] op_sel:[0,1,0]
	v_pk_fma_f32 v[250:251], v[8:9], v[60:61], v[250:251] op_sel_hi:[1,0,1]
	v_pk_fma_f32 v[252:253], v[8:9], v[68:69], v[252:253] op_sel_hi:[1,0,1]
	v_pk_fma_f32 v[250:251], v[10:11], v[60:61], v[250:251] op_sel:[0,1,0]
	v_pk_fma_f32 v[252:253], v[10:11], v[68:69], v[252:253] op_sel:[0,1,0]
	v_pk_fma_f32 v[250:251], v[12:13], v[62:63], v[250:251] op_sel_hi:[1,0,1]
	v_pk_fma_f32 v[252:253], v[12:13], v[70:71], v[252:253] op_sel_hi:[1,0,1]
	v_pk_fma_f32 v[250:251], v[14:15], v[62:63], v[250:251] op_sel:[0,1,0]
	v_pk_fma_f32 v[252:253], v[14:15], v[70:71], v[252:253] op_sel:[0,1,0]
	v_pk_fma_f32 v[0:1], v[244:245], v[80:81], v[0:1] op_sel_hi:[1,0,1]
	v_add_f32_dpp v250, v250, v250 quad_perm:[1,0,3,2] row_mask:0xf bank_mask:0xf bound_ctrl:1
	v_add_f32_dpp v251, v251, v251 quad_perm:[1,0,3,2] row_mask:0xf bank_mask:0xf bound_ctrl:1
	v_add_f32_dpp v252, v252, v252 quad_perm:[1,0,3,2] row_mask:0xf bank_mask:0xf bound_ctrl:1
	v_add_f32_dpp v253, v253, v253 quad_perm:[1,0,3,2] row_mask:0xf bank_mask:0xf bound_ctrl:1
	v_pk_fma_f32 v[2:3], v[244:245], v[80:81], v[2:3] op_sel:[0,1,0]
	v_pk_fma_f32 v[4:5], v[244:245], v[82:83], v[4:5] op_sel_hi:[1,0,1]
	v_add_f32_dpp v250, v250, v250 quad_perm:[2,3,0,1] row_mask:0xf bank_mask:0xf bound_ctrl:1
	v_add_f32_dpp v251, v251, v251 quad_perm:[2,3,0,1] row_mask:0xf bank_mask:0xf bound_ctrl:1
	v_add_f32_dpp v252, v252, v252 quad_perm:[2,3,0,1] row_mask:0xf bank_mask:0xf bound_ctrl:1
	v_add_f32_dpp v253, v253, v253 quad_perm:[2,3,0,1] row_mask:0xf bank_mask:0xf bound_ctrl:1
	v_pk_fma_f32 v[6:7], v[244:245], v[82:83], v[6:7] op_sel:[0,1,0]
	v_pk_fma_f32 v[8:9], v[244:245], v[84:85], v[8:9] op_sel_hi:[1,0,1]
	v_add_f32_dpp v250, v250, v250 row_half_mirror row_mask:0xf bank_mask:0xf bound_ctrl:1
	v_add_f32_dpp v251, v251, v251 row_half_mirror row_mask:0xf bank_mask:0xf bound_ctrl:1
	v_add_f32_dpp v252, v252, v252 row_half_mirror row_mask:0xf bank_mask:0xf bound_ctrl:1
	v_add_f32_dpp v253, v253, v253 row_half_mirror row_mask:0xf bank_mask:0xf bound_ctrl:1
	v_pk_fma_f32 v[10:11], v[244:245], v[84:85], v[10:11] op_sel:[0,1,0]
	v_pk_fma_f32 v[12:13], v[244:245], v[86:87], v[12:13] op_sel_hi:[1,0,1]
	v_pk_fma_f32 v[14:15], v[244:245], v[86:87], v[14:15] op_sel:[0,1,0]
	v_pk_fma_f32 v[0:1], v[250:251], v[72:73], v[0:1] op_sel_hi:[1,0,1]
	v_pk_fma_f32 v[2:3], v[250:251], v[72:73], v[2:3] op_sel:[0,1,0]
	v_pk_fma_f32 v[4:5], v[250:251], v[74:75], v[4:5] op_sel_hi:[1,0,1]
	v_pk_fma_f32 v[6:7], v[250:251], v[74:75], v[6:7] op_sel:[0,1,0]
	v_pk_fma_f32 v[8:9], v[250:251], v[76:77], v[8:9] op_sel_hi:[1,0,1]
	v_pk_fma_f32 v[10:11], v[250:251], v[76:77], v[10:11] op_sel:[0,1,0]
	v_pk_fma_f32 v[12:13], v[250:251], v[78:79], v[12:13] op_sel_hi:[1,0,1]
	v_pk_fma_f32 v[14:15], v[250:251], v[78:79], v[14:15] op_sel:[0,1,0]
	v_pk_fma_f32 v[248:249], v[250:251], v[246:247], v[252:253] op_sel_hi:[1,0,1]
	v_pk_fma_f32 v[248:249], v[244:245], v[246:247], v[248:249] op_sel:[0,1,0]
	s_mov_b64 exec, s[98:99]
	ds_write_b64 v201, v[248:249] offset:50944
	s_mov_b64 exec, -1
	s_waitcnt lgkmcnt(0)
	v_pk_mul_f32 v[0:1], v[0:1], v[16:17] op_sel_hi:[1,0]
	v_pk_mul_f32 v[2:3], v[2:3], v[16:17] op_sel:[0,1]
	v_pk_mul_f32 v[4:5], v[4:5], v[18:19] op_sel_hi:[1,0]
	v_pk_mul_f32 v[6:7], v[6:7], v[18:19] op_sel:[0,1]
	v_pk_mul_f32 v[8:9], v[8:9], v[20:21] op_sel_hi:[1,0]
	v_pk_mul_f32 v[10:11], v[10:11], v[20:21] op_sel:[0,1]
	v_pk_mul_f32 v[12:13], v[12:13], v[22:23] op_sel_hi:[1,0]
	v_pk_mul_f32 v[14:15], v[14:15], v[22:23] op_sel:[0,1]
	v_add_u32_e32 v200, 0x800, v200
	v_add_u32_e32 v201, 0x800, v201
	v_add_u32_e32 v202, 0x80, v202
	v_add_u32_e32 v203, 0x100, v203
	s_add_i32 s100, s100, -1
	s_cmp_lg_u32 s100, 0
	s_cbranch_scc1 .Lsc_loop
	s_branch .LBB0_931

; #define STAGE(P, BASE, br, kt) do { const char* _gb = (const char*)(BASE) + ((size_t)(br) * K + (size_t)(kt) * BK) * 2; \
;     __builtin_amdgcn_global_load_lds((const unsigned*)(_gb + loff0), (unsigned*)((char*)(P) + tid * 16), 16, 0, 0); \
;     __builtin_amdgcn_global_load_lds((const unsigned*)(_gb + (size_t)K * 128 + loff0), (unsigned*)((char*)(P) + tid * 16 + 8192), 16, 0, 0); } while (0)
; #define WAIT_V(n) asm volatile("s_waitcnt vmcnt(" #n ")" ::: "memory")
; #define BAR __builtin_amdgcn_s_barrier()
; template <int EPI> ...
;     ...
;   WAIT_V(4); BAR;
;   STAGE(SB(1, 0), Bt, bcol, 1); STAGE(SA(1, 0), A, brow, 1); STAGE(SB(1, 1), Bt, bcol + HALF, 1);
;   WAIT_V(6); BAR;
.LBB0_1017:
	s_or_b64 exec, exec, s[68:69]
	v_readfirstlane_b32 s59, v143
	v_lshl_add_u64 v[6:7], v[0:1], 0, s[10:11]
	s_mov_b32 m0, s59
	v_readfirstlane_b32 s59, v144
	s_waitcnt vmcnt(4)
	s_barrier
	global_load_lds_dwordx4 v[6:7], off
	v_lshl_add_u64 v[0:1], v[0:1], 0, s[12:13]
	s_mov_b32 m0, s59
	v_readfirstlane_b32 s59, v145
	global_load_lds_dwordx4 v[0:1], off
	v_lshl_add_u64 v[0:1], v[2:3], 0, s[10:11]
	s_mov_b32 m0, s59
	v_readfirstlane_b32 s59, v146
	global_load_lds_dwordx4 v[0:1], off
	v_lshl_add_u64 v[0:1], v[2:3], 0, s[12:13]
	s_mov_b32 m0, s59
	v_readfirstlane_b32 s59, v147
	global_load_lds_dwordx4 v[0:1], off
	v_lshl_add_u64 v[0:1], v[4:5], 0, s[10:11]
	s_mov_b32 m0, s59
	v_readfirstlane_b32 s59, v148
	global_load_lds_dwordx4 v[0:1], off
	v_lshl_add_u64 v[0:1], v[4:5], 0, s[12:13]
	s_mov_b32 m0, s59
	s_add_u32 s64, s6, s64
	global_load_lds_dwordx4 v[0:1], off
	s_addc_u32 s65, s7, s65
	s_add_u32 s66, s6, s66
	v_mov_b32_e32 v0, 0
	s_addc_u32 s67, s7, s67
	s_mov_b32 s59, -2
	v_mov_b32_e32 v1, v0
	v_mov_b32_e32 v2, v0
	v_mov_b32_e32 v3, v0
	v_mov_b32_e32 v4, v0
	v_mov_b32_e32 v5, v0
	v_mov_b32_e32 v6, v0
	v_mov_b32_e32 v7, v0
	v_mov_b32_e32 v8, v0
	v_mov_b32_e32 v9, v0
	v_mov_b32_e32 v10, v0
	v_mov_b32_e32 v11, v0
	v_mov_b32_e32 v12, v0
	v_mov_b32_e32 v13, v0
	v_mov_b32_e32 v14, v0
	v_mov_b32_e32 v15, v0
	v_mov_b32_e32 v16, v0
	v_mov_b32_e32 v17, v0
	v_mov_b32_e32 v18, v0
	v_mov_b32_e32 v19, v0
	v_mov_b32_e32 v20, v0
	v_mov_b32_e32 v21, v0
	v_mov_b32_e32 v22, v0
	v_mov_b32_e32 v23, v0
	v_mov_b32_e32 v24, v0
	v_mov_b32_e32 v25, v0
	v_mov_b32_e32 v26, v0
	v_mov_b32_e32 v27, v0
	v_mov_b32_e32 v28, v0
	v_mov_b32_e32 v29, v0
	v_mov_b32_e32 v30, v0
	v_mov_b32_e32 v31, v0
	v_mov_b32_e32 v32, v0
	v_mov_b32_e32 v33, v0
	v_mov_b32_e32 v34, v0
	v_mov_b32_e32 v35, v0
	v_mov_b32_e32 v36, v0
	v_mov_b32_e32 v37, v0
	v_mov_b32_e32 v38, v0
	v_mov_b32_e32 v39, v0
	v_mov_b32_e32 v40, v0
	v_mov_b32_e32 v41, v0
	v_mov_b32_e32 v42, v0
	v_mov_b32_e32 v43, v0
	v_mov_b32_e32 v44, v0
	v_mov_b32_e32 v45, v0
	v_mov_b32_e32 v46, v0
	v_mov_b32_e32 v47, v0
	v_mov_b32_e32 v48, v0
	v_mov_b32_e32 v49, v0
	v_mov_b32_e32 v50, v0
	v_mov_b32_e32 v51, v0
	v_mov_b32_e32 v52, v0
	v_mov_b32_e32 v53, v0
	v_mov_b32_e32 v54, v0
	v_mov_b32_e32 v55, v0
	v_mov_b32_e32 v56, v0
	v_mov_b32_e32 v57, v0
	v_mov_b32_e32 v58, v0
	v_mov_b32_e32 v59, v0
	v_mov_b32_e32 v60, v0
	v_mov_b32_e32 v61, v0
	v_mov_b32_e32 v62, v0
	v_mov_b32_e32 v63, v0
	v_mov_b32_e32 v64, v0
	v_mov_b32_e32 v65, v0
	v_mov_b32_e32 v66, v0
	v_mov_b32_e32 v67, v0
	v_mov_b32_e32 v68, v0
	v_mov_b32_e32 v69, v0
	v_mov_b32_e32 v70, v0
	v_mov_b32_e32 v71, v0
	v_mov_b32_e32 v72, v0
	v_mov_b32_e32 v73, v0
	v_mov_b32_e32 v74, v0
	v_mov_b32_e32 v75, v0
	v_mov_b32_e32 v76, v0
	v_mov_b32_e32 v77, v0
	v_mov_b32_e32 v78, v0
	v_mov_b32_e32 v79, v0
	v_mov_b32_e32 v80, v0
	v_mov_b32_e32 v81, v0
	v_mov_b32_e32 v82, v0
	v_mov_b32_e32 v83, v0
	v_mov_b32_e32 v84, v0
	v_mov_b32_e32 v85, v0
	v_mov_b32_e32 v86, v0
	v_mov_b32_e32 v87, v0
	v_mov_b32_e32 v88, v0
	v_mov_b32_e32 v89, v0
	v_mov_b32_e32 v90, v0
	v_mov_b32_e32 v91, v0
	v_mov_b32_e32 v92, v0
	v_mov_b32_e32 v93, v0
	v_mov_b32_e32 v94, v0
	v_mov_b32_e32 v95, v0
	v_mov_b32_e32 v96, v0
	v_mov_b32_e32 v97, v0
	v_mov_b32_e32 v98, v0
	v_mov_b32_e32 v99, v0
	v_mov_b32_e32 v100, v0
	v_mov_b32_e32 v101, v0
	v_mov_b32_e32 v102, v0
	v_mov_b32_e32 v103, v0
	v_mov_b32_e32 v104, v0
	v_mov_b32_e32 v105, v0
	v_mov_b32_e32 v106, v0
	v_mov_b32_e32 v107, v0
	v_mov_b32_e32 v108, v0
	v_mov_b32_e32 v109, v0
	v_mov_b32_e32 v110, v0
	v_mov_b32_e32 v111, v0
	v_mov_b32_e32 v112, v0
	v_mov_b32_e32 v113, v0
	v_mov_b32_e32 v114, v0
	v_mov_b32_e32 v115, v0
	v_mov_b32_e32 v116, v0
	v_mov_b32_e32 v117, v0
	v_mov_b32_e32 v118, v0
	v_mov_b32_e32 v119, v0
	v_mov_b32_e32 v120, v0
	v_mov_b32_e32 v121, v0
	v_mov_b32_e32 v122, v0
	v_mov_b32_e32 v123, v0
	v_mov_b32_e32 v124, v0
	v_mov_b32_e32 v125, v0
	v_mov_b32_e32 v126, v0
	v_mov_b32_e32 v127, v0
	s_waitcnt vmcnt(6)
	s_barrier

; #define STAGE(P, BASE, br, kt) do { const char* _gb = (const char*)(BASE) + ((size_t)(br) * K + (size_t)(kt) * BK) * 2; \
;     __builtin_amdgcn_global_load_lds((const unsigned*)(_gb + loff0), (unsigned*)((char*)(P) + tid * 16), 16, 0, 0); \
;     __builtin_amdgcn_global_load_lds((const unsigned*)(_gb + (size_t)K * 128 + loff0), (unsigned*)((char*)(P) + tid * 16 + 8192), 16, 0, 0); } while (0)
; #define WAIT_V(n) asm volatile("s_waitcnt vmcnt(" #n ")" ::: "memory")
; #define BAR __builtin_amdgcn_s_barrier()
; template <int EPI> ...
;     ...
;   WAIT_V(4); BAR;
;   STAGE(SB(1, 0), Bt, bcol, 1); STAGE(SA(1, 0), A, brow, 1); STAGE(SB(1, 1), Bt, bcol + HALF, 1);
;   WAIT_V(6); BAR;
.LBB0_1104:
	s_or_b64 exec, exec, s[70:71]
	v_readfirstlane_b32 s65, v144
	v_lshl_add_u64 v[6:7], v[0:1], 0, s[12:13]
	s_mov_b32 m0, s65
	v_readfirstlane_b32 s65, v145
	s_waitcnt vmcnt(4)
	s_barrier
	global_load_lds_dwordx4 v[6:7], off
	v_lshl_add_u64 v[0:1], v[0:1], 0, s[16:17]
	s_mov_b32 m0, s65
	v_readfirstlane_b32 s65, v146
	global_load_lds_dwordx4 v[0:1], off
	v_lshl_add_u64 v[0:1], v[2:3], 0, s[12:13]
	s_mov_b32 m0, s65
	v_readfirstlane_b32 s65, v147
	global_load_lds_dwordx4 v[0:1], off
	v_lshl_add_u64 v[0:1], v[2:3], 0, s[16:17]
	s_mov_b32 m0, s65
	v_readfirstlane_b32 s65, v148
	global_load_lds_dwordx4 v[0:1], off
	v_lshl_add_u64 v[0:1], v[4:5], 0, s[12:13]
	s_mov_b32 m0, s65
	v_readfirstlane_b32 s65, v149
	global_load_lds_dwordx4 v[0:1], off
	v_lshl_add_u64 v[0:1], v[4:5], 0, s[16:17]
	s_mov_b32 m0, s65
	s_add_u32 s66, s6, s66
	global_load_lds_dwordx4 v[0:1], off
	s_addc_u32 s67, s7, s67
	s_add_u32 s68, s6, s68
	v_mov_b32_e32 v0, 0
	s_addc_u32 s69, s7, s69
	s_mov_b32 s65, -2
	v_mov_b32_e32 v1, v0
	v_mov_b32_e32 v2, v0
	v_mov_b32_e32 v3, v0
	v_mov_b32_e32 v4, v0
	v_mov_b32_e32 v5, v0
	v_mov_b32_e32 v6, v0
	v_mov_b32_e32 v7, v0
	v_mov_b32_e32 v8, v0
	v_mov_b32_e32 v9, v0
	v_mov_b32_e32 v10, v0
	v_mov_b32_e32 v11, v0
	v_mov_b32_e32 v12, v0
	v_mov_b32_e32 v13, v0
	v_mov_b32_e32 v14, v0
	v_mov_b32_e32 v15, v0
	v_mov_b32_e32 v16, v0
	v_mov_b32_e32 v17, v0
	v_mov_b32_e32 v18, v0
	v_mov_b32_e32 v19, v0
	v_mov_b32_e32 v20, v0
	v_mov_b32_e32 v21, v0
	v_mov_b32_e32 v22, v0
	v_mov_b32_e32 v23, v0
	v_mov_b32_e32 v24, v0
	v_mov_b32_e32 v25, v0
	v_mov_b32_e32 v26, v0
	v_mov_b32_e32 v27, v0
	v_mov_b32_e32 v28, v0
	v_mov_b32_e32 v29, v0
	v_mov_b32_e32 v30, v0
	v_mov_b32_e32 v31, v0
	v_mov_b32_e32 v32, v0
	v_mov_b32_e32 v33, v0
	v_mov_b32_e32 v34, v0
	v_mov_b32_e32 v35, v0
	v_mov_b32_e32 v36, v0
	v_mov_b32_e32 v37, v0
	v_mov_b32_e32 v38, v0
	v_mov_b32_e32 v39, v0
	v_mov_b32_e32 v40, v0
	v_mov_b32_e32 v41, v0
	v_mov_b32_e32 v42, v0
	v_mov_b32_e32 v43, v0
	v_mov_b32_e32 v44, v0
	v_mov_b32_e32 v45, v0
	v_mov_b32_e32 v46, v0
	v_mov_b32_e32 v47, v0
	v_mov_b32_e32 v48, v0
	v_mov_b32_e32 v49, v0
	v_mov_b32_e32 v50, v0
	v_mov_b32_e32 v51, v0
	v_mov_b32_e32 v52, v0
	v_mov_b32_e32 v53, v0
	v_mov_b32_e32 v54, v0
	v_mov_b32_e32 v55, v0
	v_mov_b32_e32 v56, v0
	v_mov_b32_e32 v57, v0
	v_mov_b32_e32 v58, v0
	v_mov_b32_e32 v59, v0
	v_mov_b32_e32 v60, v0
	v_mov_b32_e32 v61, v0
	v_mov_b32_e32 v62, v0
	v_mov_b32_e32 v63, v0
	v_mov_b32_e32 v64, v0
	v_mov_b32_e32 v65, v0
	v_mov_b32_e32 v66, v0
	v_mov_b32_e32 v67, v0
	v_mov_b32_e32 v68, v0
	v_mov_b32_e32 v69, v0
	v_mov_b32_e32 v70, v0
	v_mov_b32_e32 v71, v0
	v_mov_b32_e32 v72, v0
	v_mov_b32_e32 v73, v0
	v_mov_b32_e32 v74, v0
	v_mov_b32_e32 v75, v0
	v_mov_b32_e32 v76, v0
	v_mov_b32_e32 v77, v0
	v_mov_b32_e32 v78, v0
	v_mov_b32_e32 v79, v0
	v_mov_b32_e32 v80, v0
	v_mov_b32_e32 v81, v0
	v_mov_b32_e32 v82, v0
	v_mov_b32_e32 v83, v0
	v_mov_b32_e32 v84, v0
	v_mov_b32_e32 v85, v0
	v_mov_b32_e32 v86, v0
	v_mov_b32_e32 v87, v0
	v_mov_b32_e32 v88, v0
	v_mov_b32_e32 v89, v0
	v_mov_b32_e32 v90, v0
	v_mov_b32_e32 v91, v0
	v_mov_b32_e32 v92, v0
	v_mov_b32_e32 v93, v0
	v_mov_b32_e32 v94, v0
	v_mov_b32_e32 v95, v0
	v_mov_b32_e32 v96, v0
	v_mov_b32_e32 v97, v0
	v_mov_b32_e32 v98, v0
	v_mov_b32_e32 v99, v0
	v_mov_b32_e32 v100, v0
	v_mov_b32_e32 v101, v0
	v_mov_b32_e32 v102, v0
	v_mov_b32_e32 v103, v0
	v_mov_b32_e32 v104, v0
	v_mov_b32_e32 v105, v0
	v_mov_b32_e32 v106, v0
	v_mov_b32_e32 v107, v0
	v_mov_b32_e32 v108, v0
	v_mov_b32_e32 v109, v0
	v_mov_b32_e32 v110, v0
	v_mov_b32_e32 v111, v0
	v_mov_b32_e32 v112, v0
	v_mov_b32_e32 v113, v0
	v_mov_b32_e32 v114, v0
	v_mov_b32_e32 v115, v0
	v_mov_b32_e32 v116, v0
	v_mov_b32_e32 v117, v0
	v_mov_b32_e32 v118, v0
	v_mov_b32_e32 v119, v0
	v_mov_b32_e32 v120, v0
	v_mov_b32_e32 v121, v0
	v_mov_b32_e32 v122, v0
	v_mov_b32_e32 v123, v0
	v_mov_b32_e32 v124, v0
	v_mov_b32_e32 v125, v0
	v_mov_b32_e32 v126, v0
	v_mov_b32_e32 v127, v0
	s_waitcnt vmcnt(6)
	s_barrier

; #define STAGE(P, BASE, br, kt) do { const char* _gb = (const char*)(BASE) + ((size_t)(br) * K + (size_t)(kt) * BK) * 2; \
;     __builtin_amdgcn_global_load_lds((const unsigned*)(_gb + loff0), (unsigned*)((char*)(P) + tid * 16), 16, 0, 0); \
;     __builtin_amdgcn_global_load_lds((const unsigned*)(_gb + (size_t)K * 128 + loff0), (unsigned*)((char*)(P) + tid * 16 + 8192), 16, 0, 0); } while (0)
; #define WAIT_V(n) asm volatile("s_waitcnt vmcnt(" #n ")" ::: "memory")
; #define BAR __builtin_amdgcn_s_barrier()
; template <int EPI> ...
;     ...
;   WAIT_V(4); BAR;
;   STAGE(SB(1, 0), Bt, bcol, 1); STAGE(SA(1, 0), A, brow, 1); STAGE(SB(1, 1), Bt, bcol + HALF, 1);
;   WAIT_V(6); BAR;
.LBB0_1151:
	s_or_b64 exec, exec, s[62:63]
	v_readfirstlane_b32 s62, v143
	v_lshl_add_u64 v[6:7], v[0:1], 0, s[10:11]
	s_mov_b32 m0, s62
	v_readfirstlane_b32 s62, v144
	s_waitcnt vmcnt(4)
	s_barrier
	global_load_lds_dwordx4 v[6:7], off
	v_lshl_add_u64 v[0:1], v[0:1], 0, s[12:13]
	s_mov_b32 m0, s62
	v_readfirstlane_b32 s62, v145
	global_load_lds_dwordx4 v[0:1], off
	v_lshl_add_u64 v[0:1], v[2:3], 0, s[10:11]
	s_mov_b32 m0, s62
	v_readfirstlane_b32 s62, v146
	global_load_lds_dwordx4 v[0:1], off
	v_lshl_add_u64 v[0:1], v[2:3], 0, s[12:13]
	s_mov_b32 m0, s62
	v_readfirstlane_b32 s62, v147
	global_load_lds_dwordx4 v[0:1], off
	v_lshl_add_u64 v[0:1], v[4:5], 0, s[10:11]
	s_mov_b32 m0, s62
	v_readfirstlane_b32 s62, v148
	global_load_lds_dwordx4 v[0:1], off
	v_lshl_add_u64 v[0:1], v[4:5], 0, s[12:13]
	s_mov_b32 m0, s62
	s_ashr_i32 s59, s58, 31
	global_load_lds_dwordx4 v[0:1], off
	s_add_u32 s60, s6, s60
	s_addc_u32 s61, s7, s61
	s_add_u32 s62, s6, s75
	s_addc_u32 s63, s7, s74
	s_add_u32 s64, s6, s64
	v_mov_b32_e32 v0, 0
	s_addc_u32 s65, s7, s65
	s_mov_b32 s74, -2
	v_mov_b32_e32 v1, v0
	v_mov_b32_e32 v2, v0
	v_mov_b32_e32 v3, v0
	v_mov_b32_e32 v4, v0
	v_mov_b32_e32 v5, v0
	v_mov_b32_e32 v6, v0
	v_mov_b32_e32 v7, v0
	v_mov_b32_e32 v8, v0
	v_mov_b32_e32 v9, v0
	v_mov_b32_e32 v10, v0
	v_mov_b32_e32 v11, v0
	v_mov_b32_e32 v12, v0
	v_mov_b32_e32 v13, v0
	v_mov_b32_e32 v14, v0
	v_mov_b32_e32 v15, v0
	v_mov_b32_e32 v16, v0
	v_mov_b32_e32 v17, v0
	v_mov_b32_e32 v18, v0
	v_mov_b32_e32 v19, v0
	v_mov_b32_e32 v20, v0
	v_mov_b32_e32 v21, v0
	v_mov_b32_e32 v22, v0
	v_mov_b32_e32 v23, v0
	v_mov_b32_e32 v24, v0
	v_mov_b32_e32 v25, v0
	v_mov_b32_e32 v26, v0
	v_mov_b32_e32 v27, v0
	v_mov_b32_e32 v28, v0
	v_mov_b32_e32 v29, v0
	v_mov_b32_e32 v30, v0
	v_mov_b32_e32 v31, v0
	v_mov_b32_e32 v32, v0
	v_mov_b32_e32 v33, v0
	v_mov_b32_e32 v34, v0
	v_mov_b32_e32 v35, v0
	v_mov_b32_e32 v36, v0
	v_mov_b32_e32 v37, v0
	v_mov_b32_e32 v38, v0
	v_mov_b32_e32 v39, v0
	v_mov_b32_e32 v40, v0
	v_mov_b32_e32 v41, v0
	v_mov_b32_e32 v42, v0
	v_mov_b32_e32 v43, v0
	v_mov_b32_e32 v44, v0
	v_mov_b32_e32 v45, v0
	v_mov_b32_e32 v46, v0
	v_mov_b32_e32 v47, v0
	v_mov_b32_e32 v48, v0
	v_mov_b32_e32 v49, v0
	v_mov_b32_e32 v50, v0
	v_mov_b32_e32 v51, v0
	v_mov_b32_e32 v52, v0
	v_mov_b32_e32 v53, v0
	v_mov_b32_e32 v54, v0
	v_mov_b32_e32 v55, v0
	v_mov_b32_e32 v56, v0
	v_mov_b32_e32 v57, v0
	v_mov_b32_e32 v58, v0
	v_mov_b32_e32 v59, v0
	v_mov_b32_e32 v60, v0
	v_mov_b32_e32 v61, v0
	v_mov_b32_e32 v62, v0
	v_mov_b32_e32 v63, v0
	v_mov_b32_e32 v64, v0
	v_mov_b32_e32 v65, v0
	v_mov_b32_e32 v66, v0
	v_mov_b32_e32 v67, v0
	v_mov_b32_e32 v68, v0
	v_mov_b32_e32 v69, v0
	v_mov_b32_e32 v70, v0
	v_mov_b32_e32 v71, v0
	v_mov_b32_e32 v72, v0
	v_mov_b32_e32 v73, v0
	v_mov_b32_e32 v74, v0
	v_mov_b32_e32 v75, v0
	v_mov_b32_e32 v76, v0
	v_mov_b32_e32 v77, v0
	v_mov_b32_e32 v78, v0
	v_mov_b32_e32 v79, v0
	v_mov_b32_e32 v80, v0
	v_mov_b32_e32 v81, v0
	v_mov_b32_e32 v82, v0
	v_mov_b32_e32 v83, v0
	v_mov_b32_e32 v84, v0
	v_mov_b32_e32 v85, v0
	v_mov_b32_e32 v86, v0
	v_mov_b32_e32 v87, v0
	v_mov_b32_e32 v88, v0
	v_mov_b32_e32 v89, v0
	v_mov_b32_e32 v90, v0
	v_mov_b32_e32 v91, v0
	v_mov_b32_e32 v92, v0
	v_mov_b32_e32 v93, v0
	v_mov_b32_e32 v94, v0
	v_mov_b32_e32 v95, v0
	v_mov_b32_e32 v96, v0
	v_mov_b32_e32 v97, v0
	v_mov_b32_e32 v98, v0
	v_mov_b32_e32 v99, v0
	v_mov_b32_e32 v100, v0
	v_mov_b32_e32 v101, v0
	v_mov_b32_e32 v102, v0
	v_mov_b32_e32 v103, v0
	v_mov_b32_e32 v104, v0
	v_mov_b32_e32 v105, v0
	v_mov_b32_e32 v106, v0
	v_mov_b32_e32 v107, v0
	v_mov_b32_e32 v108, v0
	v_mov_b32_e32 v109, v0
	v_mov_b32_e32 v110, v0
	v_mov_b32_e32 v111, v0
	v_mov_b32_e32 v112, v0
	v_mov_b32_e32 v113, v0
	v_mov_b32_e32 v114, v0
	v_mov_b32_e32 v115, v0
	v_mov_b32_e32 v116, v0
	v_mov_b32_e32 v117, v0
	v_mov_b32_e32 v118, v0
	v_mov_b32_e32 v119, v0
	v_mov_b32_e32 v120, v0
	v_mov_b32_e32 v121, v0
	v_mov_b32_e32 v122, v0
	v_mov_b32_e32 v123, v0
	v_mov_b32_e32 v124, v0
	v_mov_b32_e32 v125, v0
	v_mov_b32_e32 v126, v0
	v_mov_b32_e32 v127, v0
	s_waitcnt vmcnt(6)
	s_barrier
